# LDS-staged split-K sample-row GEMM pieces (DMA row slices, swizzled, hand-written MFMA loop) in P2/P9/P11/P14/P17
# speedup vs baseline: 1.0085x; 1.0085x over previous
.LBB0_342:
	s_cmpk_gt_i32 s2, 0xaf
	v_readfirstlane_b32 s7, v231
	s_cbranch_scc1 .LBB0_358
	v_and_b32_e32 v64, 63, v231
	v_and_b32_e32 v65, 15, v64
	v_bfe_u32 v66, v64, 4, 2
	v_readfirstlane_b32 s44, v230
	s_and_b32 s47, s2, 7
	s_lshr_b32 s58, s2, 3
	s_lshl_b32 s60, s58, 9
	s_nop 0
	s_and_b32 s45, s44, 3
	s_lshr_b32 s46, s44, 2
	v_and_b32_e32 v67, 3, v65
	v_xor_b32_e32 v67, v66, v67
	v_lshlrev_b32_e32 v67, 4, v67
	v_lshl_add_u32 v67, v65, 9, v67
	v_lshrrev_b32_e32 v69, 2, v65
	s_lshl_b32 s61, s45, 14
	s_lshl_b32 s62, s46, 15
	s_add_u32 s62, s62, 0x10000
	v_xor_b32_e32 v70, 0, v69
	v_lshl_add_u32 v70, v70, 6, v67
	v_add_u32_e32 v74, s62, v70
	v_add_u32_e32 v70, s61, v70
	v_xor_b32_e32 v71, 1, v69
	v_lshl_add_u32 v71, v71, 6, v67
	v_add_u32_e32 v75, s62, v71
	v_add_u32_e32 v71, s61, v71
	v_xor_b32_e32 v72, 2, v69
	v_lshl_add_u32 v72, v72, 6, v67
	v_add_u32_e32 v76, s62, v72
	v_add_u32_e32 v72, s61, v72
	v_xor_b32_e32 v73, 3, v69
	v_lshl_add_u32 v73, v73, 6, v67
	v_add_u32_e32 v77, s62, v73
	v_add_u32_e32 v73, s61, v73
	v_lshrrev_b32_e32 v68, 5, v64
	s_lshl_b32 s63, s44, 1
	v_add_u32_e32 v69, s63, v68
	v_and_b32_e32 v67, 31, v64
	v_xor_b32_e32 v67, v67, v69
	v_lshlrev_b32_e32 v67, 4, v67
	v_mul_u32_u24_e32 v68, 0x2c00, v68
	v_add_u32_e32 v68, v68, v67
	v_lshlrev_b32_e32 v69, 13, v65
	v_lshl_add_u32 v69, v66, 4, v69
	s_lshl_b32 s59, s44, 1
	s_mul_i32 s59, s59, 0x2c00
	s_add_u32 s36, s28, 0x1d300000
	s_addc_u32 s37, s29, 0
	s_add_u32 s36, s36, 0x5800000
	s_addc_u32 s37, s37, 0
	s_add_u32 s36, s36, s59
	s_addc_u32 s37, s37, 0
	s_add_u32 s36, s36, s60
	s_addc_u32 s37, s37, 0
	s_lshl_b32 s61, s47, 8
	s_mul_i32 s61, s61, 0x2c00
	s_add_u32 s38, s28, 0x2c00000
	s_addc_u32 s39, s29, 0
	s_add_u32 s38, s38, s61
	s_addc_u32 s39, s39, 0
	s_add_u32 s38, s38, s59
	s_addc_u32 s39, s39, 0
	s_add_u32 s38, s38, s60
	s_addc_u32 s39, s39, 0
	s_lshl_b32 s62, s58, 7
	s_lshl_b32 s63, s45, 5
	s_add_u32 s62, s62, s63
	s_lshl_b32 s62, s62, 13
	s_lshl_b32 s63, s47, 10
	s_lshl_b32 s3, s46, 8
	s_add_u32 s62, s62, s63
	s_add_u32 s62, s62, s3
	s_add_u32 s40, s28, 0x2ec00000
	s_addc_u32 s41, s29, 0
	s_add_u32 s40, s40, s62
	s_addc_u32 s41, s41, 0
	s_add_u32 s42, s40, 0x20000
	s_addc_u32 s43, s41, 0
	s_lshl_b32 s59, s44, 10
	s_mov_b64 s[10:11], s[36:37]
	s_add_u32 s12, s59, 0x0
	s_mov_b32 m0, s12
	s_add_u32 s12, s12, 0x2000
	global_load_lds_dwordx4 v68, s[10:11]
	s_add_u32 s10, s10, 0x2c000
	s_addc_u32 s11, s11, 0
	s_mov_b32 m0, s12
	s_add_u32 s12, s12, 0x2000
	global_load_lds_dwordx4 v68, s[10:11]
	s_add_u32 s10, s10, 0x2c000
	s_addc_u32 s11, s11, 0
	s_mov_b32 m0, s12
	s_add_u32 s12, s12, 0x2000
	global_load_lds_dwordx4 v68, s[10:11]
	s_add_u32 s10, s10, 0x2c000
	s_addc_u32 s11, s11, 0
	s_mov_b32 m0, s12
	s_add_u32 s12, s12, 0x2000
	global_load_lds_dwordx4 v68, s[10:11]
	s_add_u32 s10, s10, 0x2c000
	s_addc_u32 s11, s11, 0
	s_mov_b32 m0, s12
	s_add_u32 s12, s12, 0x2000
	global_load_lds_dwordx4 v68, s[10:11]
	s_add_u32 s10, s10, 0x2c000
	s_addc_u32 s11, s11, 0
	s_mov_b32 m0, s12
	s_add_u32 s12, s12, 0x2000
	global_load_lds_dwordx4 v68, s[10:11]
	s_add_u32 s10, s10, 0x2c000
	s_addc_u32 s11, s11, 0
	s_mov_b32 m0, s12
	s_add_u32 s12, s12, 0x2000
	global_load_lds_dwordx4 v68, s[10:11]
	s_add_u32 s10, s10, 0x2c000
	s_addc_u32 s11, s11, 0
	s_mov_b32 m0, s12
	s_add_u32 s12, s12, 0x2000
	global_load_lds_dwordx4 v68, s[10:11]
	s_add_u32 s10, s10, 0x2c000
	s_addc_u32 s11, s11, 0
	s_mov_b64 s[10:11], s[38:39]
	s_add_u32 s12, s59, 0x10000
	s_mov_b32 m0, s12
	s_add_u32 s12, s12, 0x2000
	global_load_lds_dwordx4 v68, s[10:11]
	s_add_u32 s10, s10, 0x2c000
	s_addc_u32 s11, s11, 0
	s_mov_b32 m0, s12
	s_add_u32 s12, s12, 0x2000
	global_load_lds_dwordx4 v68, s[10:11]
	s_add_u32 s10, s10, 0x2c000
	s_addc_u32 s11, s11, 0
	s_mov_b32 m0, s12
	s_add_u32 s12, s12, 0x2000
	global_load_lds_dwordx4 v68, s[10:11]
	s_add_u32 s10, s10, 0x2c000
	s_addc_u32 s11, s11, 0
	s_mov_b32 m0, s12
	s_add_u32 s12, s12, 0x2000
	global_load_lds_dwordx4 v68, s[10:11]
	s_add_u32 s10, s10, 0x2c000
	s_addc_u32 s11, s11, 0
	s_mov_b32 m0, s12
	s_add_u32 s12, s12, 0x2000
	global_load_lds_dwordx4 v68, s[10:11]
	s_add_u32 s10, s10, 0x2c000
	s_addc_u32 s11, s11, 0
	s_mov_b32 m0, s12
	s_add_u32 s12, s12, 0x2000
	global_load_lds_dwordx4 v68, s[10:11]
	s_add_u32 s10, s10, 0x2c000
	s_addc_u32 s11, s11, 0
	s_mov_b32 m0, s12
	s_add_u32 s12, s12, 0x2000
	global_load_lds_dwordx4 v68, s[10:11]
	s_add_u32 s10, s10, 0x2c000
	s_addc_u32 s11, s11, 0
	s_mov_b32 m0, s12
	s_add_u32 s12, s12, 0x2000
	global_load_lds_dwordx4 v68, s[10:11]
	s_add_u32 s10, s10, 0x2c000
	s_addc_u32 s11, s11, 0
	s_add_u32 s38, s38, 0x160000
	s_addc_u32 s39, s39, 0
	s_waitcnt vmcnt(0)
	s_barrier
	ds_read_b128 v[84:87], v70 offset:0
	ds_read_b128 v[88:91], v70 offset:8192
	ds_read_b128 v[92:95], v74 offset:0
	ds_read_b128 v[96:99], v74 offset:8192
	ds_read_b128 v[100:103], v74 offset:16384
	ds_read_b128 v[104:107], v74 offset:24576
	ds_read_b128 v[108:111], v71 offset:0
	ds_read_b128 v[112:115], v71 offset:8192
	ds_read_b128 v[116:119], v75 offset:0
	ds_read_b128 v[120:123], v75 offset:8192
	ds_read_b128 v[124:127], v75 offset:16384
	ds_read_b128 v[128:131], v75 offset:24576
	s_waitcnt lgkmcnt(6)
	v_mfma_f32_16x16x32_bf16 v[0:3], v[92:95], v[84:87], 0
	v_mfma_f32_16x16x32_bf16 v[4:7], v[96:99], v[84:87], 0
	v_mfma_f32_16x16x32_bf16 v[8:11], v[100:103], v[84:87], 0
	v_mfma_f32_16x16x32_bf16 v[12:15], v[104:107], v[84:87], 0
	v_mfma_f32_16x16x32_bf16 v[32:35], v[92:95], v[88:91], 0
	v_mfma_f32_16x16x32_bf16 v[36:39], v[96:99], v[88:91], 0
	v_mfma_f32_16x16x32_bf16 v[40:43], v[100:103], v[88:91], 0
	v_mfma_f32_16x16x32_bf16 v[44:47], v[104:107], v[88:91], 0
	ds_read_b128 v[84:87], v72 offset:0
	ds_read_b128 v[88:91], v72 offset:8192
	ds_read_b128 v[92:95], v76 offset:0
	ds_read_b128 v[96:99], v76 offset:8192
	ds_read_b128 v[100:103], v76 offset:16384
	ds_read_b128 v[104:107], v76 offset:24576
	s_waitcnt lgkmcnt(6)
	v_mfma_f32_16x16x32_bf16 v[0:3], v[116:119], v[108:111], v[0:3]
	v_mfma_f32_16x16x32_bf16 v[4:7], v[120:123], v[108:111], v[4:7]
	v_mfma_f32_16x16x32_bf16 v[8:11], v[124:127], v[108:111], v[8:11]
	v_mfma_f32_16x16x32_bf16 v[12:15], v[128:131], v[108:111], v[12:15]
	v_mfma_f32_16x16x32_bf16 v[32:35], v[116:119], v[112:115], v[32:35]
	v_mfma_f32_16x16x32_bf16 v[36:39], v[120:123], v[112:115], v[36:39]
	v_mfma_f32_16x16x32_bf16 v[40:43], v[124:127], v[112:115], v[40:43]
	v_mfma_f32_16x16x32_bf16 v[44:47], v[128:131], v[112:115], v[44:47]
	ds_read_b128 v[108:111], v73 offset:0
	ds_read_b128 v[112:115], v73 offset:8192
	ds_read_b128 v[116:119], v77 offset:0
	ds_read_b128 v[120:123], v77 offset:8192
	ds_read_b128 v[124:127], v77 offset:16384
	ds_read_b128 v[128:131], v77 offset:24576
	s_waitcnt lgkmcnt(6)
	v_mfma_f32_16x16x32_bf16 v[0:3], v[92:95], v[84:87], v[0:3]
	v_mfma_f32_16x16x32_bf16 v[4:7], v[96:99], v[84:87], v[4:7]
	v_mfma_f32_16x16x32_bf16 v[8:11], v[100:103], v[84:87], v[8:11]
	v_mfma_f32_16x16x32_bf16 v[12:15], v[104:107], v[84:87], v[12:15]
	v_mfma_f32_16x16x32_bf16 v[32:35], v[92:95], v[88:91], v[32:35]
	v_mfma_f32_16x16x32_bf16 v[36:39], v[96:99], v[88:91], v[36:39]
	v_mfma_f32_16x16x32_bf16 v[40:43], v[100:103], v[88:91], v[40:43]
	v_mfma_f32_16x16x32_bf16 v[44:47], v[104:107], v[88:91], v[44:47]
	ds_read_b128 v[84:87], v70 offset:256
	ds_read_b128 v[88:91], v70 offset:8448
	ds_read_b128 v[92:95], v74 offset:256
	ds_read_b128 v[96:99], v74 offset:8448
	ds_read_b128 v[100:103], v74 offset:16640
	ds_read_b128 v[104:107], v74 offset:24832
	s_waitcnt lgkmcnt(6)
	v_mfma_f32_16x16x32_bf16 v[0:3], v[116:119], v[108:111], v[0:3]
	v_mfma_f32_16x16x32_bf16 v[4:7], v[120:123], v[108:111], v[4:7]
	v_mfma_f32_16x16x32_bf16 v[8:11], v[124:127], v[108:111], v[8:11]
	v_mfma_f32_16x16x32_bf16 v[12:15], v[128:131], v[108:111], v[12:15]
	v_mfma_f32_16x16x32_bf16 v[32:35], v[116:119], v[112:115], v[32:35]
	v_mfma_f32_16x16x32_bf16 v[36:39], v[120:123], v[112:115], v[36:39]
	v_mfma_f32_16x16x32_bf16 v[40:43], v[124:127], v[112:115], v[40:43]
	v_mfma_f32_16x16x32_bf16 v[44:47], v[128:131], v[112:115], v[44:47]
	ds_read_b128 v[108:111], v71 offset:256
	ds_read_b128 v[112:115], v71 offset:8448
	ds_read_b128 v[116:119], v75 offset:256
	ds_read_b128 v[120:123], v75 offset:8448
	ds_read_b128 v[124:127], v75 offset:16640
	ds_read_b128 v[128:131], v75 offset:24832
	s_waitcnt lgkmcnt(6)
	v_mfma_f32_16x16x32_bf16 v[0:3], v[92:95], v[84:87], v[0:3]
	v_mfma_f32_16x16x32_bf16 v[4:7], v[96:99], v[84:87], v[4:7]
	v_mfma_f32_16x16x32_bf16 v[8:11], v[100:103], v[84:87], v[8:11]
	v_mfma_f32_16x16x32_bf16 v[12:15], v[104:107], v[84:87], v[12:15]
	v_mfma_f32_16x16x32_bf16 v[32:35], v[92:95], v[88:91], v[32:35]
	v_mfma_f32_16x16x32_bf16 v[36:39], v[96:99], v[88:91], v[36:39]
	v_mfma_f32_16x16x32_bf16 v[40:43], v[100:103], v[88:91], v[40:43]
	v_mfma_f32_16x16x32_bf16 v[44:47], v[104:107], v[88:91], v[44:47]
	ds_read_b128 v[84:87], v72 offset:256
	ds_read_b128 v[88:91], v72 offset:8448
	ds_read_b128 v[92:95], v76 offset:256
	ds_read_b128 v[96:99], v76 offset:8448
	ds_read_b128 v[100:103], v76 offset:16640
	ds_read_b128 v[104:107], v76 offset:24832
	s_waitcnt lgkmcnt(6)
	v_mfma_f32_16x16x32_bf16 v[0:3], v[116:119], v[108:111], v[0:3]
	v_mfma_f32_16x16x32_bf16 v[4:7], v[120:123], v[108:111], v[4:7]
	v_mfma_f32_16x16x32_bf16 v[8:11], v[124:127], v[108:111], v[8:11]
	v_mfma_f32_16x16x32_bf16 v[12:15], v[128:131], v[108:111], v[12:15]
	v_mfma_f32_16x16x32_bf16 v[32:35], v[116:119], v[112:115], v[32:35]
	v_mfma_f32_16x16x32_bf16 v[36:39], v[120:123], v[112:115], v[36:39]
	v_mfma_f32_16x16x32_bf16 v[40:43], v[124:127], v[112:115], v[40:43]
	v_mfma_f32_16x16x32_bf16 v[44:47], v[128:131], v[112:115], v[44:47]
	ds_read_b128 v[108:111], v73 offset:256
	ds_read_b128 v[112:115], v73 offset:8448
	ds_read_b128 v[116:119], v77 offset:256
	ds_read_b128 v[120:123], v77 offset:8448
	ds_read_b128 v[124:127], v77 offset:16640
	ds_read_b128 v[128:131], v77 offset:24832
	s_waitcnt lgkmcnt(6)
	v_mfma_f32_16x16x32_bf16 v[0:3], v[92:95], v[84:87], v[0:3]
	v_mfma_f32_16x16x32_bf16 v[4:7], v[96:99], v[84:87], v[4:7]
	v_mfma_f32_16x16x32_bf16 v[8:11], v[100:103], v[84:87], v[8:11]
	v_mfma_f32_16x16x32_bf16 v[12:15], v[104:107], v[84:87], v[12:15]
	v_mfma_f32_16x16x32_bf16 v[32:35], v[92:95], v[88:91], v[32:35]
	v_mfma_f32_16x16x32_bf16 v[36:39], v[96:99], v[88:91], v[36:39]
	v_mfma_f32_16x16x32_bf16 v[40:43], v[100:103], v[88:91], v[40:43]
	v_mfma_f32_16x16x32_bf16 v[44:47], v[104:107], v[88:91], v[44:47]
	s_waitcnt lgkmcnt(0)
	v_mfma_f32_16x16x32_bf16 v[0:3], v[116:119], v[108:111], v[0:3]
	v_mfma_f32_16x16x32_bf16 v[4:7], v[120:123], v[108:111], v[4:7]
	v_mfma_f32_16x16x32_bf16 v[8:11], v[124:127], v[108:111], v[8:11]
	v_mfma_f32_16x16x32_bf16 v[12:15], v[128:131], v[108:111], v[12:15]
	v_mfma_f32_16x16x32_bf16 v[32:35], v[116:119], v[112:115], v[32:35]
	v_mfma_f32_16x16x32_bf16 v[36:39], v[120:123], v[112:115], v[36:39]
	v_mfma_f32_16x16x32_bf16 v[40:43], v[124:127], v[112:115], v[40:43]
	v_mfma_f32_16x16x32_bf16 v[44:47], v[128:131], v[112:115], v[44:47]
	s_barrier
	s_mov_b64 s[10:11], s[38:39]
	s_add_u32 s12, s59, 0x10000
	s_mov_b32 m0, s12
	s_add_u32 s12, s12, 0x2000
	global_load_lds_dwordx4 v68, s[10:11]
	s_add_u32 s10, s10, 0x2c000
	s_addc_u32 s11, s11, 0
	s_mov_b32 m0, s12
	s_add_u32 s12, s12, 0x2000
	global_load_lds_dwordx4 v68, s[10:11]
	s_add_u32 s10, s10, 0x2c000
	s_addc_u32 s11, s11, 0
	s_mov_b32 m0, s12
	s_add_u32 s12, s12, 0x2000
	global_load_lds_dwordx4 v68, s[10:11]
	s_add_u32 s10, s10, 0x2c000
	s_addc_u32 s11, s11, 0
	s_mov_b32 m0, s12
	s_add_u32 s12, s12, 0x2000
	global_load_lds_dwordx4 v68, s[10:11]
	s_add_u32 s10, s10, 0x2c000
	s_addc_u32 s11, s11, 0
	s_mov_b32 m0, s12
	s_add_u32 s12, s12, 0x2000
	global_load_lds_dwordx4 v68, s[10:11]
	s_add_u32 s10, s10, 0x2c000
	s_addc_u32 s11, s11, 0
	s_mov_b32 m0, s12
	s_add_u32 s12, s12, 0x2000
	global_load_lds_dwordx4 v68, s[10:11]
	s_add_u32 s10, s10, 0x2c000
	s_addc_u32 s11, s11, 0
	s_mov_b32 m0, s12
	s_add_u32 s12, s12, 0x2000
	global_load_lds_dwordx4 v68, s[10:11]
	s_add_u32 s10, s10, 0x2c000
	s_addc_u32 s11, s11, 0
	s_mov_b32 m0, s12
	s_add_u32 s12, s12, 0x2000
	global_load_lds_dwordx4 v68, s[10:11]
	s_add_u32 s10, s10, 0x2c000
	s_addc_u32 s11, s11, 0
	s_waitcnt vmcnt(0)
	s_barrier
	ds_read_b128 v[84:87], v70 offset:0
	ds_read_b128 v[88:91], v70 offset:8192
	ds_read_b128 v[92:95], v74 offset:0
	ds_read_b128 v[96:99], v74 offset:8192
	ds_read_b128 v[100:103], v74 offset:16384
	ds_read_b128 v[104:107], v74 offset:24576
	ds_read_b128 v[108:111], v71 offset:0
	ds_read_b128 v[112:115], v71 offset:8192
	ds_read_b128 v[116:119], v75 offset:0
	ds_read_b128 v[120:123], v75 offset:8192
	ds_read_b128 v[124:127], v75 offset:16384
	ds_read_b128 v[128:131], v75 offset:24576
	s_waitcnt lgkmcnt(6)
	v_mfma_f32_16x16x32_bf16 v[16:19], v[92:95], v[84:87], 0
	v_mfma_f32_16x16x32_bf16 v[20:23], v[96:99], v[84:87], 0
	v_mfma_f32_16x16x32_bf16 v[24:27], v[100:103], v[84:87], 0
	v_mfma_f32_16x16x32_bf16 v[28:31], v[104:107], v[84:87], 0
	v_mfma_f32_16x16x32_bf16 v[48:51], v[92:95], v[88:91], 0
	v_mfma_f32_16x16x32_bf16 v[52:55], v[96:99], v[88:91], 0
	v_mfma_f32_16x16x32_bf16 v[56:59], v[100:103], v[88:91], 0
	v_mfma_f32_16x16x32_bf16 v[60:63], v[104:107], v[88:91], 0
	ds_read_b128 v[84:87], v72 offset:0
	ds_read_b128 v[88:91], v72 offset:8192
	ds_read_b128 v[92:95], v76 offset:0
	ds_read_b128 v[96:99], v76 offset:8192
	ds_read_b128 v[100:103], v76 offset:16384
	ds_read_b128 v[104:107], v76 offset:24576
	s_waitcnt lgkmcnt(6)
	v_mfma_f32_16x16x32_bf16 v[16:19], v[116:119], v[108:111], v[16:19]
	v_mfma_f32_16x16x32_bf16 v[20:23], v[120:123], v[108:111], v[20:23]
	v_mfma_f32_16x16x32_bf16 v[24:27], v[124:127], v[108:111], v[24:27]
	v_mfma_f32_16x16x32_bf16 v[28:31], v[128:131], v[108:111], v[28:31]
	v_mfma_f32_16x16x32_bf16 v[48:51], v[116:119], v[112:115], v[48:51]
	v_mfma_f32_16x16x32_bf16 v[52:55], v[120:123], v[112:115], v[52:55]
	v_mfma_f32_16x16x32_bf16 v[56:59], v[124:127], v[112:115], v[56:59]
	v_mfma_f32_16x16x32_bf16 v[60:63], v[128:131], v[112:115], v[60:63]
	ds_read_b128 v[108:111], v73 offset:0
	ds_read_b128 v[112:115], v73 offset:8192
	ds_read_b128 v[116:119], v77 offset:0
	ds_read_b128 v[120:123], v77 offset:8192
	ds_read_b128 v[124:127], v77 offset:16384
	ds_read_b128 v[128:131], v77 offset:24576
	s_waitcnt lgkmcnt(6)
	v_mfma_f32_16x16x32_bf16 v[16:19], v[92:95], v[84:87], v[16:19]
	v_mfma_f32_16x16x32_bf16 v[20:23], v[96:99], v[84:87], v[20:23]
	v_mfma_f32_16x16x32_bf16 v[24:27], v[100:103], v[84:87], v[24:27]
	v_mfma_f32_16x16x32_bf16 v[28:31], v[104:107], v[84:87], v[28:31]
	v_mfma_f32_16x16x32_bf16 v[48:51], v[92:95], v[88:91], v[48:51]
	v_mfma_f32_16x16x32_bf16 v[52:55], v[96:99], v[88:91], v[52:55]
	v_mfma_f32_16x16x32_bf16 v[56:59], v[100:103], v[88:91], v[56:59]
	v_mfma_f32_16x16x32_bf16 v[60:63], v[104:107], v[88:91], v[60:63]
	ds_read_b128 v[84:87], v70 offset:256
	ds_read_b128 v[88:91], v70 offset:8448
	ds_read_b128 v[92:95], v74 offset:256
	ds_read_b128 v[96:99], v74 offset:8448
	ds_read_b128 v[100:103], v74 offset:16640
	ds_read_b128 v[104:107], v74 offset:24832
	s_waitcnt lgkmcnt(6)
	v_mfma_f32_16x16x32_bf16 v[16:19], v[116:119], v[108:111], v[16:19]
	v_mfma_f32_16x16x32_bf16 v[20:23], v[120:123], v[108:111], v[20:23]
	v_mfma_f32_16x16x32_bf16 v[24:27], v[124:127], v[108:111], v[24:27]
	v_mfma_f32_16x16x32_bf16 v[28:31], v[128:131], v[108:111], v[28:31]
	v_mfma_f32_16x16x32_bf16 v[48:51], v[116:119], v[112:115], v[48:51]
	v_mfma_f32_16x16x32_bf16 v[52:55], v[120:123], v[112:115], v[52:55]
	v_mfma_f32_16x16x32_bf16 v[56:59], v[124:127], v[112:115], v[56:59]
	v_mfma_f32_16x16x32_bf16 v[60:63], v[128:131], v[112:115], v[60:63]
	ds_read_b128 v[108:111], v71 offset:256
	ds_read_b128 v[112:115], v71 offset:8448
	ds_read_b128 v[116:119], v75 offset:256
	ds_read_b128 v[120:123], v75 offset:8448
	ds_read_b128 v[124:127], v75 offset:16640
	ds_read_b128 v[128:131], v75 offset:24832
	s_waitcnt lgkmcnt(6)
	v_mfma_f32_16x16x32_bf16 v[16:19], v[92:95], v[84:87], v[16:19]
	v_mfma_f32_16x16x32_bf16 v[20:23], v[96:99], v[84:87], v[20:23]
	v_mfma_f32_16x16x32_bf16 v[24:27], v[100:103], v[84:87], v[24:27]
	v_mfma_f32_16x16x32_bf16 v[28:31], v[104:107], v[84:87], v[28:31]
	v_mfma_f32_16x16x32_bf16 v[48:51], v[92:95], v[88:91], v[48:51]
	v_mfma_f32_16x16x32_bf16 v[52:55], v[96:99], v[88:91], v[52:55]
	v_mfma_f32_16x16x32_bf16 v[56:59], v[100:103], v[88:91], v[56:59]
	v_mfma_f32_16x16x32_bf16 v[60:63], v[104:107], v[88:91], v[60:63]
	ds_read_b128 v[84:87], v72 offset:256
	ds_read_b128 v[88:91], v72 offset:8448
	ds_read_b128 v[92:95], v76 offset:256
	ds_read_b128 v[96:99], v76 offset:8448
	ds_read_b128 v[100:103], v76 offset:16640
	ds_read_b128 v[104:107], v76 offset:24832
	s_waitcnt lgkmcnt(6)
	v_mfma_f32_16x16x32_bf16 v[16:19], v[116:119], v[108:111], v[16:19]
	v_mfma_f32_16x16x32_bf16 v[20:23], v[120:123], v[108:111], v[20:23]
	v_mfma_f32_16x16x32_bf16 v[24:27], v[124:127], v[108:111], v[24:27]
	v_mfma_f32_16x16x32_bf16 v[28:31], v[128:131], v[108:111], v[28:31]
	v_mfma_f32_16x16x32_bf16 v[48:51], v[116:119], v[112:115], v[48:51]
	v_mfma_f32_16x16x32_bf16 v[52:55], v[120:123], v[112:115], v[52:55]
	v_mfma_f32_16x16x32_bf16 v[56:59], v[124:127], v[112:115], v[56:59]
	v_mfma_f32_16x16x32_bf16 v[60:63], v[128:131], v[112:115], v[60:63]
	ds_read_b128 v[108:111], v73 offset:256
	ds_read_b128 v[112:115], v73 offset:8448
	ds_read_b128 v[116:119], v77 offset:256
	ds_read_b128 v[120:123], v77 offset:8448
	ds_read_b128 v[124:127], v77 offset:16640
	ds_read_b128 v[128:131], v77 offset:24832
	s_waitcnt lgkmcnt(6)
	v_mfma_f32_16x16x32_bf16 v[16:19], v[92:95], v[84:87], v[16:19]
	v_mfma_f32_16x16x32_bf16 v[20:23], v[96:99], v[84:87], v[20:23]
	v_mfma_f32_16x16x32_bf16 v[24:27], v[100:103], v[84:87], v[24:27]
	v_mfma_f32_16x16x32_bf16 v[28:31], v[104:107], v[84:87], v[28:31]
	v_mfma_f32_16x16x32_bf16 v[48:51], v[92:95], v[88:91], v[48:51]
	v_mfma_f32_16x16x32_bf16 v[52:55], v[96:99], v[88:91], v[52:55]
	v_mfma_f32_16x16x32_bf16 v[56:59], v[100:103], v[88:91], v[56:59]
	v_mfma_f32_16x16x32_bf16 v[60:63], v[104:107], v[88:91], v[60:63]
	s_waitcnt lgkmcnt(0)
	v_mfma_f32_16x16x32_bf16 v[16:19], v[116:119], v[108:111], v[16:19]
	v_mfma_f32_16x16x32_bf16 v[20:23], v[120:123], v[108:111], v[20:23]
	v_mfma_f32_16x16x32_bf16 v[24:27], v[124:127], v[108:111], v[24:27]
	v_mfma_f32_16x16x32_bf16 v[28:31], v[128:131], v[108:111], v[28:31]
	v_mfma_f32_16x16x32_bf16 v[48:51], v[116:119], v[112:115], v[48:51]
	v_mfma_f32_16x16x32_bf16 v[52:55], v[120:123], v[112:115], v[52:55]
	v_mfma_f32_16x16x32_bf16 v[56:59], v[124:127], v[112:115], v[56:59]
	v_mfma_f32_16x16x32_bf16 v[60:63], v[128:131], v[112:115], v[60:63]
	s_nop 7
	global_store_dwordx4 v69, v[0:3], s[40:41] offset:0
	global_store_dwordx4 v69, v[4:7], s[40:41] offset:64
	global_store_dwordx4 v69, v[8:11], s[40:41] offset:128
	global_store_dwordx4 v69, v[12:15], s[40:41] offset:192
	global_store_dwordx4 v69, v[16:19], s[40:41] offset:512
	global_store_dwordx4 v69, v[20:23], s[40:41] offset:576
	global_store_dwordx4 v69, v[24:27], s[40:41] offset:640
	global_store_dwordx4 v69, v[28:31], s[40:41] offset:704
	global_store_dwordx4 v69, v[32:35], s[42:43] offset:0
	global_store_dwordx4 v69, v[36:39], s[42:43] offset:64
	global_store_dwordx4 v69, v[40:43], s[42:43] offset:128
	global_store_dwordx4 v69, v[44:47], s[42:43] offset:192
	global_store_dwordx4 v69, v[48:51], s[42:43] offset:512
	global_store_dwordx4 v69, v[52:55], s[42:43] offset:576
	global_store_dwordx4 v69, v[56:59], s[42:43] offset:640
	global_store_dwordx4 v69, v[60:63], s[42:43] offset:704

.LBB0_1656:
	s_cmp_gt_i32 s2, 63
	v_readfirstlane_b32 s10, v231
	s_cbranch_scc1 .LBB0_1672
	v_and_b32_e32 v64, 63, v231
	v_and_b32_e32 v65, 15, v64
	v_bfe_u32 v66, v64, 4, 2
	v_readfirstlane_b32 s44, v230
	s_and_b32 s47, s2, 7
	s_lshr_b32 s58, s2, 3
	s_lshl_b32 s60, s58, 9
	s_nop 0
	s_and_b32 s45, s44, 3
	s_lshr_b32 s46, s44, 2
	v_and_b32_e32 v67, 3, v65
	v_xor_b32_e32 v67, v66, v67
	v_lshlrev_b32_e32 v67, 4, v67
	v_lshl_add_u32 v67, v65, 9, v67
	v_lshrrev_b32_e32 v69, 2, v65
	s_lshl_b32 s61, s45, 14
	s_lshl_b32 s62, s46, 15
	s_add_u32 s62, s62, 0x10000
	v_xor_b32_e32 v70, 0, v69
	v_lshl_add_u32 v70, v70, 6, v67
	v_add_u32_e32 v74, s62, v70
	v_add_u32_e32 v70, s61, v70
	v_xor_b32_e32 v71, 1, v69
	v_lshl_add_u32 v71, v71, 6, v67
	v_add_u32_e32 v75, s62, v71
	v_add_u32_e32 v71, s61, v71
	v_xor_b32_e32 v72, 2, v69
	v_lshl_add_u32 v72, v72, 6, v67
	v_add_u32_e32 v76, s62, v72
	v_add_u32_e32 v72, s61, v72
	v_xor_b32_e32 v73, 3, v69
	v_lshl_add_u32 v73, v73, 6, v67
	v_add_u32_e32 v77, s62, v73
	v_add_u32_e32 v73, s61, v73
	v_lshrrev_b32_e32 v68, 5, v64
	s_lshl_b32 s63, s44, 1
	v_add_u32_e32 v69, s63, v68
	v_and_b32_e32 v67, 31, v64
	v_xor_b32_e32 v67, v67, v69
	v_lshlrev_b32_e32 v67, 4, v67
	v_mul_u32_u24_e32 v68, 0x1000, v68
	v_add_u32_e32 v68, v68, v67
	v_lshlrev_b32_e32 v69, 13, v65
	v_lshl_add_u32 v69, v66, 4, v69
	s_lshl_b32 s59, s44, 1
	s_mul_i32 s59, s59, 0x1000
	s_add_u32 s36, s28, 0x2bf00000
	s_addc_u32 s37, s29, 0
	s_add_u32 s36, s36, 0x2000000
	s_addc_u32 s37, s37, 0
	s_add_u32 s36, s36, s59
	s_addc_u32 s37, s37, 0
	s_add_u32 s36, s36, s60
	s_addc_u32 s37, s37, 0
	s_lshl_b32 s61, s47, 8
	s_mul_i32 s61, s61, 0x1000
	s_add_u32 s38, s28, 0x5800000
	s_addc_u32 s39, s29, 0
	s_add_u32 s38, s38, s61
	s_addc_u32 s39, s39, 0
	s_add_u32 s38, s38, s59
	s_addc_u32 s39, s39, 0
	s_add_u32 s38, s38, s60
	s_addc_u32 s39, s39, 0
	s_lshl_b32 s62, s58, 7
	s_lshl_b32 s63, s45, 5
	s_add_u32 s62, s62, s63
	s_lshl_b32 s62, s62, 13
	s_lshl_b32 s63, s47, 10
	s_lshl_b32 s3, s46, 8
	s_add_u32 s62, s62, s63
	s_add_u32 s62, s62, s3
	s_add_u32 s40, s28, 0x2ec00000
	s_addc_u32 s41, s29, 0
	s_add_u32 s40, s40, s62
	s_addc_u32 s41, s41, 0
	s_add_u32 s42, s40, 0x20000
	s_addc_u32 s43, s41, 0
	s_lshl_b32 s59, s44, 10
	s_mov_b64 s[10:11], s[36:37]
	s_add_u32 s12, s59, 0x0
	s_mov_b32 m0, s12
	s_add_u32 s12, s12, 0x2000
	global_load_lds_dwordx4 v68, s[10:11]
	s_add_u32 s10, s10, 0x10000
	s_addc_u32 s11, s11, 0
	s_mov_b32 m0, s12
	s_add_u32 s12, s12, 0x2000
	global_load_lds_dwordx4 v68, s[10:11]
	s_add_u32 s10, s10, 0x10000
	s_addc_u32 s11, s11, 0
	s_mov_b32 m0, s12
	s_add_u32 s12, s12, 0x2000
	global_load_lds_dwordx4 v68, s[10:11]
	s_add_u32 s10, s10, 0x10000
	s_addc_u32 s11, s11, 0
	s_mov_b32 m0, s12
	s_add_u32 s12, s12, 0x2000
	global_load_lds_dwordx4 v68, s[10:11]
	s_add_u32 s10, s10, 0x10000
	s_addc_u32 s11, s11, 0
	s_mov_b32 m0, s12
	s_add_u32 s12, s12, 0x2000
	global_load_lds_dwordx4 v68, s[10:11]
	s_add_u32 s10, s10, 0x10000
	s_addc_u32 s11, s11, 0
	s_mov_b32 m0, s12
	s_add_u32 s12, s12, 0x2000
	global_load_lds_dwordx4 v68, s[10:11]
	s_add_u32 s10, s10, 0x10000
	s_addc_u32 s11, s11, 0
	s_mov_b32 m0, s12
	s_add_u32 s12, s12, 0x2000
	global_load_lds_dwordx4 v68, s[10:11]
	s_add_u32 s10, s10, 0x10000
	s_addc_u32 s11, s11, 0
	s_mov_b32 m0, s12
	s_add_u32 s12, s12, 0x2000
	global_load_lds_dwordx4 v68, s[10:11]
	s_add_u32 s10, s10, 0x10000
	s_addc_u32 s11, s11, 0
	s_mov_b64 s[10:11], s[38:39]
	s_add_u32 s12, s59, 0x10000
	s_mov_b32 m0, s12
	s_add_u32 s12, s12, 0x2000
	global_load_lds_dwordx4 v68, s[10:11]
	s_add_u32 s10, s10, 0x10000
	s_addc_u32 s11, s11, 0
	s_mov_b32 m0, s12
	s_add_u32 s12, s12, 0x2000
	global_load_lds_dwordx4 v68, s[10:11]
	s_add_u32 s10, s10, 0x10000
	s_addc_u32 s11, s11, 0
	s_mov_b32 m0, s12
	s_add_u32 s12, s12, 0x2000
	global_load_lds_dwordx4 v68, s[10:11]
	s_add_u32 s10, s10, 0x10000
	s_addc_u32 s11, s11, 0
	s_mov_b32 m0, s12
	s_add_u32 s12, s12, 0x2000
	global_load_lds_dwordx4 v68, s[10:11]
	s_add_u32 s10, s10, 0x10000
	s_addc_u32 s11, s11, 0
	s_mov_b32 m0, s12
	s_add_u32 s12, s12, 0x2000
	global_load_lds_dwordx4 v68, s[10:11]
	s_add_u32 s10, s10, 0x10000
	s_addc_u32 s11, s11, 0
	s_mov_b32 m0, s12
	s_add_u32 s12, s12, 0x2000
	global_load_lds_dwordx4 v68, s[10:11]
	s_add_u32 s10, s10, 0x10000
	s_addc_u32 s11, s11, 0
	s_mov_b32 m0, s12
	s_add_u32 s12, s12, 0x2000
	global_load_lds_dwordx4 v68, s[10:11]
	s_add_u32 s10, s10, 0x10000
	s_addc_u32 s11, s11, 0
	s_mov_b32 m0, s12
	s_add_u32 s12, s12, 0x2000
	global_load_lds_dwordx4 v68, s[10:11]
	s_add_u32 s10, s10, 0x10000
	s_addc_u32 s11, s11, 0
	s_add_u32 s38, s38, 0x80000
	s_addc_u32 s39, s39, 0
	s_waitcnt vmcnt(0)
	s_barrier
	ds_read_b128 v[84:87], v70 offset:0
	ds_read_b128 v[88:91], v70 offset:8192
	ds_read_b128 v[92:95], v74 offset:0
	ds_read_b128 v[96:99], v74 offset:8192
	ds_read_b128 v[100:103], v74 offset:16384
	ds_read_b128 v[104:107], v74 offset:24576
	ds_read_b128 v[108:111], v71 offset:0
	ds_read_b128 v[112:115], v71 offset:8192
	ds_read_b128 v[116:119], v75 offset:0
	ds_read_b128 v[120:123], v75 offset:8192
	ds_read_b128 v[124:127], v75 offset:16384
	ds_read_b128 v[128:131], v75 offset:24576
	s_waitcnt lgkmcnt(6)
	v_mfma_f32_16x16x32_bf16 v[0:3], v[92:95], v[84:87], 0
	v_mfma_f32_16x16x32_bf16 v[4:7], v[96:99], v[84:87], 0
	v_mfma_f32_16x16x32_bf16 v[8:11], v[100:103], v[84:87], 0
	v_mfma_f32_16x16x32_bf16 v[12:15], v[104:107], v[84:87], 0
	v_mfma_f32_16x16x32_bf16 v[32:35], v[92:95], v[88:91], 0
	v_mfma_f32_16x16x32_bf16 v[36:39], v[96:99], v[88:91], 0
	v_mfma_f32_16x16x32_bf16 v[40:43], v[100:103], v[88:91], 0
	v_mfma_f32_16x16x32_bf16 v[44:47], v[104:107], v[88:91], 0
	ds_read_b128 v[84:87], v72 offset:0
	ds_read_b128 v[88:91], v72 offset:8192
	ds_read_b128 v[92:95], v76 offset:0
	ds_read_b128 v[96:99], v76 offset:8192
	ds_read_b128 v[100:103], v76 offset:16384
	ds_read_b128 v[104:107], v76 offset:24576
	s_waitcnt lgkmcnt(6)
	v_mfma_f32_16x16x32_bf16 v[0:3], v[116:119], v[108:111], v[0:3]
	v_mfma_f32_16x16x32_bf16 v[4:7], v[120:123], v[108:111], v[4:7]
	v_mfma_f32_16x16x32_bf16 v[8:11], v[124:127], v[108:111], v[8:11]
	v_mfma_f32_16x16x32_bf16 v[12:15], v[128:131], v[108:111], v[12:15]
	v_mfma_f32_16x16x32_bf16 v[32:35], v[116:119], v[112:115], v[32:35]
	v_mfma_f32_16x16x32_bf16 v[36:39], v[120:123], v[112:115], v[36:39]
	v_mfma_f32_16x16x32_bf16 v[40:43], v[124:127], v[112:115], v[40:43]
	v_mfma_f32_16x16x32_bf16 v[44:47], v[128:131], v[112:115], v[44:47]
	ds_read_b128 v[108:111], v73 offset:0
	ds_read_b128 v[112:115], v73 offset:8192
	ds_read_b128 v[116:119], v77 offset:0
	ds_read_b128 v[120:123], v77 offset:8192
	ds_read_b128 v[124:127], v77 offset:16384
	ds_read_b128 v[128:131], v77 offset:24576
	s_waitcnt lgkmcnt(6)
	v_mfma_f32_16x16x32_bf16 v[0:3], v[92:95], v[84:87], v[0:3]
	v_mfma_f32_16x16x32_bf16 v[4:7], v[96:99], v[84:87], v[4:7]
	v_mfma_f32_16x16x32_bf16 v[8:11], v[100:103], v[84:87], v[8:11]
	v_mfma_f32_16x16x32_bf16 v[12:15], v[104:107], v[84:87], v[12:15]
	v_mfma_f32_16x16x32_bf16 v[32:35], v[92:95], v[88:91], v[32:35]
	v_mfma_f32_16x16x32_bf16 v[36:39], v[96:99], v[88:91], v[36:39]
	v_mfma_f32_16x16x32_bf16 v[40:43], v[100:103], v[88:91], v[40:43]
	v_mfma_f32_16x16x32_bf16 v[44:47], v[104:107], v[88:91], v[44:47]
	ds_read_b128 v[84:87], v70 offset:256
	ds_read_b128 v[88:91], v70 offset:8448
	ds_read_b128 v[92:95], v74 offset:256
	ds_read_b128 v[96:99], v74 offset:8448
	ds_read_b128 v[100:103], v74 offset:16640
	ds_read_b128 v[104:107], v74 offset:24832
	s_waitcnt lgkmcnt(6)
	v_mfma_f32_16x16x32_bf16 v[0:3], v[116:119], v[108:111], v[0:3]
	v_mfma_f32_16x16x32_bf16 v[4:7], v[120:123], v[108:111], v[4:7]
	v_mfma_f32_16x16x32_bf16 v[8:11], v[124:127], v[108:111], v[8:11]
	v_mfma_f32_16x16x32_bf16 v[12:15], v[128:131], v[108:111], v[12:15]
	v_mfma_f32_16x16x32_bf16 v[32:35], v[116:119], v[112:115], v[32:35]
	v_mfma_f32_16x16x32_bf16 v[36:39], v[120:123], v[112:115], v[36:39]
	v_mfma_f32_16x16x32_bf16 v[40:43], v[124:127], v[112:115], v[40:43]
	v_mfma_f32_16x16x32_bf16 v[44:47], v[128:131], v[112:115], v[44:47]
	ds_read_b128 v[108:111], v71 offset:256
	ds_read_b128 v[112:115], v71 offset:8448
	ds_read_b128 v[116:119], v75 offset:256
	ds_read_b128 v[120:123], v75 offset:8448
	ds_read_b128 v[124:127], v75 offset:16640
	ds_read_b128 v[128:131], v75 offset:24832
	s_waitcnt lgkmcnt(6)
	v_mfma_f32_16x16x32_bf16 v[0:3], v[92:95], v[84:87], v[0:3]
	v_mfma_f32_16x16x32_bf16 v[4:7], v[96:99], v[84:87], v[4:7]
	v_mfma_f32_16x16x32_bf16 v[8:11], v[100:103], v[84:87], v[8:11]
	v_mfma_f32_16x16x32_bf16 v[12:15], v[104:107], v[84:87], v[12:15]
	v_mfma_f32_16x16x32_bf16 v[32:35], v[92:95], v[88:91], v[32:35]
	v_mfma_f32_16x16x32_bf16 v[36:39], v[96:99], v[88:91], v[36:39]
	v_mfma_f32_16x16x32_bf16 v[40:43], v[100:103], v[88:91], v[40:43]
	v_mfma_f32_16x16x32_bf16 v[44:47], v[104:107], v[88:91], v[44:47]
	ds_read_b128 v[84:87], v72 offset:256
	ds_read_b128 v[88:91], v72 offset:8448
	ds_read_b128 v[92:95], v76 offset:256
	ds_read_b128 v[96:99], v76 offset:8448
	ds_read_b128 v[100:103], v76 offset:16640
	ds_read_b128 v[104:107], v76 offset:24832
	s_waitcnt lgkmcnt(6)
	v_mfma_f32_16x16x32_bf16 v[0:3], v[116:119], v[108:111], v[0:3]
	v_mfma_f32_16x16x32_bf16 v[4:7], v[120:123], v[108:111], v[4:7]
	v_mfma_f32_16x16x32_bf16 v[8:11], v[124:127], v[108:111], v[8:11]
	v_mfma_f32_16x16x32_bf16 v[12:15], v[128:131], v[108:111], v[12:15]
	v_mfma_f32_16x16x32_bf16 v[32:35], v[116:119], v[112:115], v[32:35]
	v_mfma_f32_16x16x32_bf16 v[36:39], v[120:123], v[112:115], v[36:39]
	v_mfma_f32_16x16x32_bf16 v[40:43], v[124:127], v[112:115], v[40:43]
	v_mfma_f32_16x16x32_bf16 v[44:47], v[128:131], v[112:115], v[44:47]
	ds_read_b128 v[108:111], v73 offset:256
	ds_read_b128 v[112:115], v73 offset:8448
	ds_read_b128 v[116:119], v77 offset:256
	ds_read_b128 v[120:123], v77 offset:8448
	ds_read_b128 v[124:127], v77 offset:16640
	ds_read_b128 v[128:131], v77 offset:24832
	s_waitcnt lgkmcnt(6)
	v_mfma_f32_16x16x32_bf16 v[0:3], v[92:95], v[84:87], v[0:3]
	v_mfma_f32_16x16x32_bf16 v[4:7], v[96:99], v[84:87], v[4:7]
	v_mfma_f32_16x16x32_bf16 v[8:11], v[100:103], v[84:87], v[8:11]
	v_mfma_f32_16x16x32_bf16 v[12:15], v[104:107], v[84:87], v[12:15]
	v_mfma_f32_16x16x32_bf16 v[32:35], v[92:95], v[88:91], v[32:35]
	v_mfma_f32_16x16x32_bf16 v[36:39], v[96:99], v[88:91], v[36:39]
	v_mfma_f32_16x16x32_bf16 v[40:43], v[100:103], v[88:91], v[40:43]
	v_mfma_f32_16x16x32_bf16 v[44:47], v[104:107], v[88:91], v[44:47]
	s_waitcnt lgkmcnt(0)
	v_mfma_f32_16x16x32_bf16 v[0:3], v[116:119], v[108:111], v[0:3]
	v_mfma_f32_16x16x32_bf16 v[4:7], v[120:123], v[108:111], v[4:7]
	v_mfma_f32_16x16x32_bf16 v[8:11], v[124:127], v[108:111], v[8:11]
	v_mfma_f32_16x16x32_bf16 v[12:15], v[128:131], v[108:111], v[12:15]
	v_mfma_f32_16x16x32_bf16 v[32:35], v[116:119], v[112:115], v[32:35]
	v_mfma_f32_16x16x32_bf16 v[36:39], v[120:123], v[112:115], v[36:39]
	v_mfma_f32_16x16x32_bf16 v[40:43], v[124:127], v[112:115], v[40:43]
	v_mfma_f32_16x16x32_bf16 v[44:47], v[128:131], v[112:115], v[44:47]
	s_barrier
	s_mov_b64 s[10:11], s[38:39]
	s_add_u32 s12, s59, 0x10000
	s_mov_b32 m0, s12
	s_add_u32 s12, s12, 0x2000
	global_load_lds_dwordx4 v68, s[10:11]
	s_add_u32 s10, s10, 0x10000
	s_addc_u32 s11, s11, 0
	s_mov_b32 m0, s12
	s_add_u32 s12, s12, 0x2000
	global_load_lds_dwordx4 v68, s[10:11]
	s_add_u32 s10, s10, 0x10000
	s_addc_u32 s11, s11, 0
	s_mov_b32 m0, s12
	s_add_u32 s12, s12, 0x2000
	global_load_lds_dwordx4 v68, s[10:11]
	s_add_u32 s10, s10, 0x10000
	s_addc_u32 s11, s11, 0
	s_mov_b32 m0, s12
	s_add_u32 s12, s12, 0x2000
	global_load_lds_dwordx4 v68, s[10:11]
	s_add_u32 s10, s10, 0x10000
	s_addc_u32 s11, s11, 0
	s_mov_b32 m0, s12
	s_add_u32 s12, s12, 0x2000
	global_load_lds_dwordx4 v68, s[10:11]
	s_add_u32 s10, s10, 0x10000
	s_addc_u32 s11, s11, 0
	s_mov_b32 m0, s12
	s_add_u32 s12, s12, 0x2000
	global_load_lds_dwordx4 v68, s[10:11]
	s_add_u32 s10, s10, 0x10000
	s_addc_u32 s11, s11, 0
	s_mov_b32 m0, s12
	s_add_u32 s12, s12, 0x2000
	global_load_lds_dwordx4 v68, s[10:11]
	s_add_u32 s10, s10, 0x10000
	s_addc_u32 s11, s11, 0
	s_mov_b32 m0, s12
	s_add_u32 s12, s12, 0x2000
	global_load_lds_dwordx4 v68, s[10:11]
	s_add_u32 s10, s10, 0x10000
	s_addc_u32 s11, s11, 0
	s_waitcnt vmcnt(0)
	s_barrier
	ds_read_b128 v[84:87], v70 offset:0
	ds_read_b128 v[88:91], v70 offset:8192
	ds_read_b128 v[92:95], v74 offset:0
	ds_read_b128 v[96:99], v74 offset:8192
	ds_read_b128 v[100:103], v74 offset:16384
	ds_read_b128 v[104:107], v74 offset:24576
	ds_read_b128 v[108:111], v71 offset:0
	ds_read_b128 v[112:115], v71 offset:8192
	ds_read_b128 v[116:119], v75 offset:0
	ds_read_b128 v[120:123], v75 offset:8192
	ds_read_b128 v[124:127], v75 offset:16384
	ds_read_b128 v[128:131], v75 offset:24576
	s_waitcnt lgkmcnt(6)
	v_mfma_f32_16x16x32_bf16 v[16:19], v[92:95], v[84:87], 0
	v_mfma_f32_16x16x32_bf16 v[20:23], v[96:99], v[84:87], 0
	v_mfma_f32_16x16x32_bf16 v[24:27], v[100:103], v[84:87], 0
	v_mfma_f32_16x16x32_bf16 v[28:31], v[104:107], v[84:87], 0
	v_mfma_f32_16x16x32_bf16 v[48:51], v[92:95], v[88:91], 0
	v_mfma_f32_16x16x32_bf16 v[52:55], v[96:99], v[88:91], 0
	v_mfma_f32_16x16x32_bf16 v[56:59], v[100:103], v[88:91], 0
	v_mfma_f32_16x16x32_bf16 v[60:63], v[104:107], v[88:91], 0
	ds_read_b128 v[84:87], v72 offset:0
	ds_read_b128 v[88:91], v72 offset:8192
	ds_read_b128 v[92:95], v76 offset:0
	ds_read_b128 v[96:99], v76 offset:8192
	ds_read_b128 v[100:103], v76 offset:16384
	ds_read_b128 v[104:107], v76 offset:24576
	s_waitcnt lgkmcnt(6)
	v_mfma_f32_16x16x32_bf16 v[16:19], v[116:119], v[108:111], v[16:19]
	v_mfma_f32_16x16x32_bf16 v[20:23], v[120:123], v[108:111], v[20:23]
	v_mfma_f32_16x16x32_bf16 v[24:27], v[124:127], v[108:111], v[24:27]
	v_mfma_f32_16x16x32_bf16 v[28:31], v[128:131], v[108:111], v[28:31]
	v_mfma_f32_16x16x32_bf16 v[48:51], v[116:119], v[112:115], v[48:51]
	v_mfma_f32_16x16x32_bf16 v[52:55], v[120:123], v[112:115], v[52:55]
	v_mfma_f32_16x16x32_bf16 v[56:59], v[124:127], v[112:115], v[56:59]
	v_mfma_f32_16x16x32_bf16 v[60:63], v[128:131], v[112:115], v[60:63]
	ds_read_b128 v[108:111], v73 offset:0
	ds_read_b128 v[112:115], v73 offset:8192
	ds_read_b128 v[116:119], v77 offset:0
	ds_read_b128 v[120:123], v77 offset:8192
	ds_read_b128 v[124:127], v77 offset:16384
	ds_read_b128 v[128:131], v77 offset:24576
	s_waitcnt lgkmcnt(6)
	v_mfma_f32_16x16x32_bf16 v[16:19], v[92:95], v[84:87], v[16:19]
	v_mfma_f32_16x16x32_bf16 v[20:23], v[96:99], v[84:87], v[20:23]
	v_mfma_f32_16x16x32_bf16 v[24:27], v[100:103], v[84:87], v[24:27]
	v_mfma_f32_16x16x32_bf16 v[28:31], v[104:107], v[84:87], v[28:31]
	v_mfma_f32_16x16x32_bf16 v[48:51], v[92:95], v[88:91], v[48:51]
	v_mfma_f32_16x16x32_bf16 v[52:55], v[96:99], v[88:91], v[52:55]
	v_mfma_f32_16x16x32_bf16 v[56:59], v[100:103], v[88:91], v[56:59]
	v_mfma_f32_16x16x32_bf16 v[60:63], v[104:107], v[88:91], v[60:63]
	ds_read_b128 v[84:87], v70 offset:256
	ds_read_b128 v[88:91], v70 offset:8448
	ds_read_b128 v[92:95], v74 offset:256
	ds_read_b128 v[96:99], v74 offset:8448
	ds_read_b128 v[100:103], v74 offset:16640
	ds_read_b128 v[104:107], v74 offset:24832
	s_waitcnt lgkmcnt(6)
	v_mfma_f32_16x16x32_bf16 v[16:19], v[116:119], v[108:111], v[16:19]
	v_mfma_f32_16x16x32_bf16 v[20:23], v[120:123], v[108:111], v[20:23]
	v_mfma_f32_16x16x32_bf16 v[24:27], v[124:127], v[108:111], v[24:27]
	v_mfma_f32_16x16x32_bf16 v[28:31], v[128:131], v[108:111], v[28:31]
	v_mfma_f32_16x16x32_bf16 v[48:51], v[116:119], v[112:115], v[48:51]
	v_mfma_f32_16x16x32_bf16 v[52:55], v[120:123], v[112:115], v[52:55]
	v_mfma_f32_16x16x32_bf16 v[56:59], v[124:127], v[112:115], v[56:59]
	v_mfma_f32_16x16x32_bf16 v[60:63], v[128:131], v[112:115], v[60:63]
	ds_read_b128 v[108:111], v71 offset:256
	ds_read_b128 v[112:115], v71 offset:8448
	ds_read_b128 v[116:119], v75 offset:256
	ds_read_b128 v[120:123], v75 offset:8448
	ds_read_b128 v[124:127], v75 offset:16640
	ds_read_b128 v[128:131], v75 offset:24832
	s_waitcnt lgkmcnt(6)
	v_mfma_f32_16x16x32_bf16 v[16:19], v[92:95], v[84:87], v[16:19]
	v_mfma_f32_16x16x32_bf16 v[20:23], v[96:99], v[84:87], v[20:23]
	v_mfma_f32_16x16x32_bf16 v[24:27], v[100:103], v[84:87], v[24:27]
	v_mfma_f32_16x16x32_bf16 v[28:31], v[104:107], v[84:87], v[28:31]
	v_mfma_f32_16x16x32_bf16 v[48:51], v[92:95], v[88:91], v[48:51]
	v_mfma_f32_16x16x32_bf16 v[52:55], v[96:99], v[88:91], v[52:55]
	v_mfma_f32_16x16x32_bf16 v[56:59], v[100:103], v[88:91], v[56:59]
	v_mfma_f32_16x16x32_bf16 v[60:63], v[104:107], v[88:91], v[60:63]
	ds_read_b128 v[84:87], v72 offset:256
	ds_read_b128 v[88:91], v72 offset:8448
	ds_read_b128 v[92:95], v76 offset:256
	ds_read_b128 v[96:99], v76 offset:8448
	ds_read_b128 v[100:103], v76 offset:16640
	ds_read_b128 v[104:107], v76 offset:24832
	s_waitcnt lgkmcnt(6)
	v_mfma_f32_16x16x32_bf16 v[16:19], v[116:119], v[108:111], v[16:19]
	v_mfma_f32_16x16x32_bf16 v[20:23], v[120:123], v[108:111], v[20:23]
	v_mfma_f32_16x16x32_bf16 v[24:27], v[124:127], v[108:111], v[24:27]
	v_mfma_f32_16x16x32_bf16 v[28:31], v[128:131], v[108:111], v[28:31]
	v_mfma_f32_16x16x32_bf16 v[48:51], v[116:119], v[112:115], v[48:51]
	v_mfma_f32_16x16x32_bf16 v[52:55], v[120:123], v[112:115], v[52:55]
	v_mfma_f32_16x16x32_bf16 v[56:59], v[124:127], v[112:115], v[56:59]
	v_mfma_f32_16x16x32_bf16 v[60:63], v[128:131], v[112:115], v[60:63]
	ds_read_b128 v[108:111], v73 offset:256
	ds_read_b128 v[112:115], v73 offset:8448
	ds_read_b128 v[116:119], v77 offset:256
	ds_read_b128 v[120:123], v77 offset:8448
	ds_read_b128 v[124:127], v77 offset:16640
	ds_read_b128 v[128:131], v77 offset:24832
	s_waitcnt lgkmcnt(6)
	v_mfma_f32_16x16x32_bf16 v[16:19], v[92:95], v[84:87], v[16:19]
	v_mfma_f32_16x16x32_bf16 v[20:23], v[96:99], v[84:87], v[20:23]
	v_mfma_f32_16x16x32_bf16 v[24:27], v[100:103], v[84:87], v[24:27]
	v_mfma_f32_16x16x32_bf16 v[28:31], v[104:107], v[84:87], v[28:31]
	v_mfma_f32_16x16x32_bf16 v[48:51], v[92:95], v[88:91], v[48:51]
	v_mfma_f32_16x16x32_bf16 v[52:55], v[96:99], v[88:91], v[52:55]
	v_mfma_f32_16x16x32_bf16 v[56:59], v[100:103], v[88:91], v[56:59]
	v_mfma_f32_16x16x32_bf16 v[60:63], v[104:107], v[88:91], v[60:63]
	s_waitcnt lgkmcnt(0)
	v_mfma_f32_16x16x32_bf16 v[16:19], v[116:119], v[108:111], v[16:19]
	v_mfma_f32_16x16x32_bf16 v[20:23], v[120:123], v[108:111], v[20:23]
	v_mfma_f32_16x16x32_bf16 v[24:27], v[124:127], v[108:111], v[24:27]
	v_mfma_f32_16x16x32_bf16 v[28:31], v[128:131], v[108:111], v[28:31]
	v_mfma_f32_16x16x32_bf16 v[48:51], v[116:119], v[112:115], v[48:51]
	v_mfma_f32_16x16x32_bf16 v[52:55], v[120:123], v[112:115], v[52:55]
	v_mfma_f32_16x16x32_bf16 v[56:59], v[124:127], v[112:115], v[56:59]
	v_mfma_f32_16x16x32_bf16 v[60:63], v[128:131], v[112:115], v[60:63]
	s_nop 7
	global_store_dwordx4 v69, v[0:3], s[40:41] offset:0
	global_store_dwordx4 v69, v[4:7], s[40:41] offset:64
	global_store_dwordx4 v69, v[8:11], s[40:41] offset:128
	global_store_dwordx4 v69, v[12:15], s[40:41] offset:192
	global_store_dwordx4 v69, v[16:19], s[40:41] offset:512
	global_store_dwordx4 v69, v[20:23], s[40:41] offset:576
	global_store_dwordx4 v69, v[24:27], s[40:41] offset:640
	global_store_dwordx4 v69, v[28:31], s[40:41] offset:704
	global_store_dwordx4 v69, v[32:35], s[42:43] offset:0
	global_store_dwordx4 v69, v[36:39], s[42:43] offset:64
	global_store_dwordx4 v69, v[40:43], s[42:43] offset:128
	global_store_dwordx4 v69, v[44:47], s[42:43] offset:192
	global_store_dwordx4 v69, v[48:51], s[42:43] offset:512
	global_store_dwordx4 v69, v[52:55], s[42:43] offset:576
	global_store_dwordx4 v69, v[56:59], s[42:43] offset:640
	global_store_dwordx4 v69, v[60:63], s[42:43] offset:704

.LBB0_1832:
	s_cmp_gt_i32 s2, 63
	v_readfirstlane_b32 s10, v231
	s_cbranch_scc1 .LBB0_1848
	v_and_b32_e32 v64, 63, v231
	v_and_b32_e32 v65, 15, v64
	v_bfe_u32 v66, v64, 4, 2
	v_readfirstlane_b32 s44, v230
	s_and_b32 s47, s2, 7
	s_lshr_b32 s58, s2, 3
	s_lshl_b32 s60, s58, 9
	s_nop 0
	s_and_b32 s45, s44, 3
	s_lshr_b32 s46, s44, 2
	v_and_b32_e32 v67, 3, v65
	v_xor_b32_e32 v67, v66, v67
	v_lshlrev_b32_e32 v67, 4, v67
	v_lshl_add_u32 v67, v65, 9, v67
	v_lshrrev_b32_e32 v69, 2, v65
	s_lshl_b32 s61, s45, 14
	s_lshl_b32 s62, s46, 15
	s_add_u32 s62, s62, 0x10000
	v_xor_b32_e32 v70, 0, v69
	v_lshl_add_u32 v70, v70, 6, v67
	v_add_u32_e32 v74, s62, v70
	v_add_u32_e32 v70, s61, v70
	v_xor_b32_e32 v71, 1, v69
	v_lshl_add_u32 v71, v71, 6, v67
	v_add_u32_e32 v75, s62, v71
	v_add_u32_e32 v71, s61, v71
	v_xor_b32_e32 v72, 2, v69
	v_lshl_add_u32 v72, v72, 6, v67
	v_add_u32_e32 v76, s62, v72
	v_add_u32_e32 v72, s61, v72
	v_xor_b32_e32 v73, 3, v69
	v_lshl_add_u32 v73, v73, 6, v67
	v_add_u32_e32 v77, s62, v73
	v_add_u32_e32 v73, s61, v73
	v_lshrrev_b32_e32 v68, 5, v64
	s_lshl_b32 s63, s44, 1
	v_add_u32_e32 v69, s63, v68
	v_and_b32_e32 v67, 31, v64
	v_xor_b32_e32 v67, v67, v69
	v_lshlrev_b32_e32 v67, 4, v67
	v_mul_u32_u24_e32 v68, 0x1000, v68
	v_add_u32_e32 v68, v68, v67
	v_lshlrev_b32_e32 v69, 13, v65
	v_lshl_add_u32 v69, v66, 4, v69
	s_lshl_b32 s59, s44, 1
	s_mul_i32 s59, s59, 0x1000
	s_add_u32 s36, s28, 0xc500000
	s_addc_u32 s37, s29, 0
	s_add_u32 s36, s36, 0x2000000
	s_addc_u32 s37, s37, 0
	s_add_u32 s36, s36, s59
	s_addc_u32 s37, s37, 0
	s_add_u32 s36, s36, s60
	s_addc_u32 s37, s37, 0
	s_lshl_b32 s61, s47, 8
	s_mul_i32 s61, s61, 0x1000
	s_add_u32 s38, s28, 0x6000000
	s_addc_u32 s39, s29, 0
	s_add_u32 s38, s38, s61
	s_addc_u32 s39, s39, 0
	s_add_u32 s38, s38, s59
	s_addc_u32 s39, s39, 0
	s_add_u32 s38, s38, s60
	s_addc_u32 s39, s39, 0
	s_lshl_b32 s62, s58, 7
	s_lshl_b32 s63, s45, 5
	s_add_u32 s62, s62, s63
	s_lshl_b32 s62, s62, 13
	s_lshl_b32 s63, s47, 10
	s_lshl_b32 s3, s46, 8
	s_add_u32 s62, s62, s63
	s_add_u32 s62, s62, s3
	s_add_u32 s40, s28, 0x2ec00000
	s_addc_u32 s41, s29, 0
	s_add_u32 s40, s40, s62
	s_addc_u32 s41, s41, 0
	s_add_u32 s42, s40, 0x20000
	s_addc_u32 s43, s41, 0
	s_lshl_b32 s59, s44, 10
	s_mov_b64 s[10:11], s[36:37]
	s_add_u32 s12, s59, 0x0
	s_mov_b32 m0, s12
	s_add_u32 s12, s12, 0x2000
	global_load_lds_dwordx4 v68, s[10:11]
	s_add_u32 s10, s10, 0x10000
	s_addc_u32 s11, s11, 0
	s_mov_b32 m0, s12
	s_add_u32 s12, s12, 0x2000
	global_load_lds_dwordx4 v68, s[10:11]
	s_add_u32 s10, s10, 0x10000
	s_addc_u32 s11, s11, 0
	s_mov_b32 m0, s12
	s_add_u32 s12, s12, 0x2000
	global_load_lds_dwordx4 v68, s[10:11]
	s_add_u32 s10, s10, 0x10000
	s_addc_u32 s11, s11, 0
	s_mov_b32 m0, s12
	s_add_u32 s12, s12, 0x2000
	global_load_lds_dwordx4 v68, s[10:11]
	s_add_u32 s10, s10, 0x10000
	s_addc_u32 s11, s11, 0
	s_mov_b32 m0, s12
	s_add_u32 s12, s12, 0x2000
	global_load_lds_dwordx4 v68, s[10:11]
	s_add_u32 s10, s10, 0x10000
	s_addc_u32 s11, s11, 0
	s_mov_b32 m0, s12
	s_add_u32 s12, s12, 0x2000
	global_load_lds_dwordx4 v68, s[10:11]
	s_add_u32 s10, s10, 0x10000
	s_addc_u32 s11, s11, 0
	s_mov_b32 m0, s12
	s_add_u32 s12, s12, 0x2000
	global_load_lds_dwordx4 v68, s[10:11]
	s_add_u32 s10, s10, 0x10000
	s_addc_u32 s11, s11, 0
	s_mov_b32 m0, s12
	s_add_u32 s12, s12, 0x2000
	global_load_lds_dwordx4 v68, s[10:11]
	s_add_u32 s10, s10, 0x10000
	s_addc_u32 s11, s11, 0
	s_mov_b64 s[10:11], s[38:39]
	s_add_u32 s12, s59, 0x10000
	s_mov_b32 m0, s12
	s_add_u32 s12, s12, 0x2000
	global_load_lds_dwordx4 v68, s[10:11]
	s_add_u32 s10, s10, 0x10000
	s_addc_u32 s11, s11, 0
	s_mov_b32 m0, s12
	s_add_u32 s12, s12, 0x2000
	global_load_lds_dwordx4 v68, s[10:11]
	s_add_u32 s10, s10, 0x10000
	s_addc_u32 s11, s11, 0
	s_mov_b32 m0, s12
	s_add_u32 s12, s12, 0x2000
	global_load_lds_dwordx4 v68, s[10:11]
	s_add_u32 s10, s10, 0x10000
	s_addc_u32 s11, s11, 0
	s_mov_b32 m0, s12
	s_add_u32 s12, s12, 0x2000
	global_load_lds_dwordx4 v68, s[10:11]
	s_add_u32 s10, s10, 0x10000
	s_addc_u32 s11, s11, 0
	s_mov_b32 m0, s12
	s_add_u32 s12, s12, 0x2000
	global_load_lds_dwordx4 v68, s[10:11]
	s_add_u32 s10, s10, 0x10000
	s_addc_u32 s11, s11, 0
	s_mov_b32 m0, s12
	s_add_u32 s12, s12, 0x2000
	global_load_lds_dwordx4 v68, s[10:11]
	s_add_u32 s10, s10, 0x10000
	s_addc_u32 s11, s11, 0
	s_mov_b32 m0, s12
	s_add_u32 s12, s12, 0x2000
	global_load_lds_dwordx4 v68, s[10:11]
	s_add_u32 s10, s10, 0x10000
	s_addc_u32 s11, s11, 0
	s_mov_b32 m0, s12
	s_add_u32 s12, s12, 0x2000
	global_load_lds_dwordx4 v68, s[10:11]
	s_add_u32 s10, s10, 0x10000
	s_addc_u32 s11, s11, 0
	s_add_u32 s38, s38, 0x80000
	s_addc_u32 s39, s39, 0
	s_waitcnt vmcnt(0)
	s_barrier
	ds_read_b128 v[84:87], v70 offset:0
	ds_read_b128 v[88:91], v70 offset:8192
	ds_read_b128 v[92:95], v74 offset:0
	ds_read_b128 v[96:99], v74 offset:8192
	ds_read_b128 v[100:103], v74 offset:16384
	ds_read_b128 v[104:107], v74 offset:24576
	ds_read_b128 v[108:111], v71 offset:0
	ds_read_b128 v[112:115], v71 offset:8192
	ds_read_b128 v[116:119], v75 offset:0
	ds_read_b128 v[120:123], v75 offset:8192
	ds_read_b128 v[124:127], v75 offset:16384
	ds_read_b128 v[128:131], v75 offset:24576
	s_waitcnt lgkmcnt(6)
	v_mfma_f32_16x16x32_bf16 v[0:3], v[92:95], v[84:87], 0
	v_mfma_f32_16x16x32_bf16 v[4:7], v[96:99], v[84:87], 0
	v_mfma_f32_16x16x32_bf16 v[8:11], v[100:103], v[84:87], 0
	v_mfma_f32_16x16x32_bf16 v[12:15], v[104:107], v[84:87], 0
	v_mfma_f32_16x16x32_bf16 v[32:35], v[92:95], v[88:91], 0
	v_mfma_f32_16x16x32_bf16 v[36:39], v[96:99], v[88:91], 0
	v_mfma_f32_16x16x32_bf16 v[40:43], v[100:103], v[88:91], 0
	v_mfma_f32_16x16x32_bf16 v[44:47], v[104:107], v[88:91], 0
	ds_read_b128 v[84:87], v72 offset:0
	ds_read_b128 v[88:91], v72 offset:8192
	ds_read_b128 v[92:95], v76 offset:0
	ds_read_b128 v[96:99], v76 offset:8192
	ds_read_b128 v[100:103], v76 offset:16384
	ds_read_b128 v[104:107], v76 offset:24576
	s_waitcnt lgkmcnt(6)
	v_mfma_f32_16x16x32_bf16 v[0:3], v[116:119], v[108:111], v[0:3]
	v_mfma_f32_16x16x32_bf16 v[4:7], v[120:123], v[108:111], v[4:7]
	v_mfma_f32_16x16x32_bf16 v[8:11], v[124:127], v[108:111], v[8:11]
	v_mfma_f32_16x16x32_bf16 v[12:15], v[128:131], v[108:111], v[12:15]
	v_mfma_f32_16x16x32_bf16 v[32:35], v[116:119], v[112:115], v[32:35]
	v_mfma_f32_16x16x32_bf16 v[36:39], v[120:123], v[112:115], v[36:39]
	v_mfma_f32_16x16x32_bf16 v[40:43], v[124:127], v[112:115], v[40:43]
	v_mfma_f32_16x16x32_bf16 v[44:47], v[128:131], v[112:115], v[44:47]
	ds_read_b128 v[108:111], v73 offset:0
	ds_read_b128 v[112:115], v73 offset:8192
	ds_read_b128 v[116:119], v77 offset:0
	ds_read_b128 v[120:123], v77 offset:8192
	ds_read_b128 v[124:127], v77 offset:16384
	ds_read_b128 v[128:131], v77 offset:24576
	s_waitcnt lgkmcnt(6)
	v_mfma_f32_16x16x32_bf16 v[0:3], v[92:95], v[84:87], v[0:3]
	v_mfma_f32_16x16x32_bf16 v[4:7], v[96:99], v[84:87], v[4:7]
	v_mfma_f32_16x16x32_bf16 v[8:11], v[100:103], v[84:87], v[8:11]
	v_mfma_f32_16x16x32_bf16 v[12:15], v[104:107], v[84:87], v[12:15]
	v_mfma_f32_16x16x32_bf16 v[32:35], v[92:95], v[88:91], v[32:35]
	v_mfma_f32_16x16x32_bf16 v[36:39], v[96:99], v[88:91], v[36:39]
	v_mfma_f32_16x16x32_bf16 v[40:43], v[100:103], v[88:91], v[40:43]
	v_mfma_f32_16x16x32_bf16 v[44:47], v[104:107], v[88:91], v[44:47]
	ds_read_b128 v[84:87], v70 offset:256
	ds_read_b128 v[88:91], v70 offset:8448
	ds_read_b128 v[92:95], v74 offset:256
	ds_read_b128 v[96:99], v74 offset:8448
	ds_read_b128 v[100:103], v74 offset:16640
	ds_read_b128 v[104:107], v74 offset:24832
	s_waitcnt lgkmcnt(6)
	v_mfma_f32_16x16x32_bf16 v[0:3], v[116:119], v[108:111], v[0:3]
	v_mfma_f32_16x16x32_bf16 v[4:7], v[120:123], v[108:111], v[4:7]
	v_mfma_f32_16x16x32_bf16 v[8:11], v[124:127], v[108:111], v[8:11]
	v_mfma_f32_16x16x32_bf16 v[12:15], v[128:131], v[108:111], v[12:15]
	v_mfma_f32_16x16x32_bf16 v[32:35], v[116:119], v[112:115], v[32:35]
	v_mfma_f32_16x16x32_bf16 v[36:39], v[120:123], v[112:115], v[36:39]
	v_mfma_f32_16x16x32_bf16 v[40:43], v[124:127], v[112:115], v[40:43]
	v_mfma_f32_16x16x32_bf16 v[44:47], v[128:131], v[112:115], v[44:47]
	ds_read_b128 v[108:111], v71 offset:256
	ds_read_b128 v[112:115], v71 offset:8448
	ds_read_b128 v[116:119], v75 offset:256
	ds_read_b128 v[120:123], v75 offset:8448
	ds_read_b128 v[124:127], v75 offset:16640
	ds_read_b128 v[128:131], v75 offset:24832
	s_waitcnt lgkmcnt(6)
	v_mfma_f32_16x16x32_bf16 v[0:3], v[92:95], v[84:87], v[0:3]
	v_mfma_f32_16x16x32_bf16 v[4:7], v[96:99], v[84:87], v[4:7]
	v_mfma_f32_16x16x32_bf16 v[8:11], v[100:103], v[84:87], v[8:11]
	v_mfma_f32_16x16x32_bf16 v[12:15], v[104:107], v[84:87], v[12:15]
	v_mfma_f32_16x16x32_bf16 v[32:35], v[92:95], v[88:91], v[32:35]
	v_mfma_f32_16x16x32_bf16 v[36:39], v[96:99], v[88:91], v[36:39]
	v_mfma_f32_16x16x32_bf16 v[40:43], v[100:103], v[88:91], v[40:43]
	v_mfma_f32_16x16x32_bf16 v[44:47], v[104:107], v[88:91], v[44:47]
	ds_read_b128 v[84:87], v72 offset:256
	ds_read_b128 v[88:91], v72 offset:8448
	ds_read_b128 v[92:95], v76 offset:256
	ds_read_b128 v[96:99], v76 offset:8448
	ds_read_b128 v[100:103], v76 offset:16640
	ds_read_b128 v[104:107], v76 offset:24832
	s_waitcnt lgkmcnt(6)
	v_mfma_f32_16x16x32_bf16 v[0:3], v[116:119], v[108:111], v[0:3]
	v_mfma_f32_16x16x32_bf16 v[4:7], v[120:123], v[108:111], v[4:7]
	v_mfma_f32_16x16x32_bf16 v[8:11], v[124:127], v[108:111], v[8:11]
	v_mfma_f32_16x16x32_bf16 v[12:15], v[128:131], v[108:111], v[12:15]
	v_mfma_f32_16x16x32_bf16 v[32:35], v[116:119], v[112:115], v[32:35]
	v_mfma_f32_16x16x32_bf16 v[36:39], v[120:123], v[112:115], v[36:39]
	v_mfma_f32_16x16x32_bf16 v[40:43], v[124:127], v[112:115], v[40:43]
	v_mfma_f32_16x16x32_bf16 v[44:47], v[128:131], v[112:115], v[44:47]
	ds_read_b128 v[108:111], v73 offset:256
	ds_read_b128 v[112:115], v73 offset:8448
	ds_read_b128 v[116:119], v77 offset:256
	ds_read_b128 v[120:123], v77 offset:8448
	ds_read_b128 v[124:127], v77 offset:16640
	ds_read_b128 v[128:131], v77 offset:24832
	s_waitcnt lgkmcnt(6)
	v_mfma_f32_16x16x32_bf16 v[0:3], v[92:95], v[84:87], v[0:3]
	v_mfma_f32_16x16x32_bf16 v[4:7], v[96:99], v[84:87], v[4:7]
	v_mfma_f32_16x16x32_bf16 v[8:11], v[100:103], v[84:87], v[8:11]
	v_mfma_f32_16x16x32_bf16 v[12:15], v[104:107], v[84:87], v[12:15]
	v_mfma_f32_16x16x32_bf16 v[32:35], v[92:95], v[88:91], v[32:35]
	v_mfma_f32_16x16x32_bf16 v[36:39], v[96:99], v[88:91], v[36:39]
	v_mfma_f32_16x16x32_bf16 v[40:43], v[100:103], v[88:91], v[40:43]
	v_mfma_f32_16x16x32_bf16 v[44:47], v[104:107], v[88:91], v[44:47]
	s_waitcnt lgkmcnt(0)
	v_mfma_f32_16x16x32_bf16 v[0:3], v[116:119], v[108:111], v[0:3]
	v_mfma_f32_16x16x32_bf16 v[4:7], v[120:123], v[108:111], v[4:7]
	v_mfma_f32_16x16x32_bf16 v[8:11], v[124:127], v[108:111], v[8:11]
	v_mfma_f32_16x16x32_bf16 v[12:15], v[128:131], v[108:111], v[12:15]
	v_mfma_f32_16x16x32_bf16 v[32:35], v[116:119], v[112:115], v[32:35]
	v_mfma_f32_16x16x32_bf16 v[36:39], v[120:123], v[112:115], v[36:39]
	v_mfma_f32_16x16x32_bf16 v[40:43], v[124:127], v[112:115], v[40:43]
	v_mfma_f32_16x16x32_bf16 v[44:47], v[128:131], v[112:115], v[44:47]
	s_barrier
	s_mov_b64 s[10:11], s[38:39]
	s_add_u32 s12, s59, 0x10000
	s_mov_b32 m0, s12
	s_add_u32 s12, s12, 0x2000
	global_load_lds_dwordx4 v68, s[10:11]
	s_add_u32 s10, s10, 0x10000
	s_addc_u32 s11, s11, 0
	s_mov_b32 m0, s12
	s_add_u32 s12, s12, 0x2000
	global_load_lds_dwordx4 v68, s[10:11]
	s_add_u32 s10, s10, 0x10000
	s_addc_u32 s11, s11, 0
	s_mov_b32 m0, s12
	s_add_u32 s12, s12, 0x2000
	global_load_lds_dwordx4 v68, s[10:11]
	s_add_u32 s10, s10, 0x10000
	s_addc_u32 s11, s11, 0
	s_mov_b32 m0, s12
	s_add_u32 s12, s12, 0x2000
	global_load_lds_dwordx4 v68, s[10:11]
	s_add_u32 s10, s10, 0x10000
	s_addc_u32 s11, s11, 0
	s_mov_b32 m0, s12
	s_add_u32 s12, s12, 0x2000
	global_load_lds_dwordx4 v68, s[10:11]
	s_add_u32 s10, s10, 0x10000
	s_addc_u32 s11, s11, 0
	s_mov_b32 m0, s12
	s_add_u32 s12, s12, 0x2000
	global_load_lds_dwordx4 v68, s[10:11]
	s_add_u32 s10, s10, 0x10000
	s_addc_u32 s11, s11, 0
	s_mov_b32 m0, s12
	s_add_u32 s12, s12, 0x2000
	global_load_lds_dwordx4 v68, s[10:11]
	s_add_u32 s10, s10, 0x10000
	s_addc_u32 s11, s11, 0
	s_mov_b32 m0, s12
	s_add_u32 s12, s12, 0x2000
	global_load_lds_dwordx4 v68, s[10:11]
	s_add_u32 s10, s10, 0x10000
	s_addc_u32 s11, s11, 0
	s_waitcnt vmcnt(0)
	s_barrier
	ds_read_b128 v[84:87], v70 offset:0
	ds_read_b128 v[88:91], v70 offset:8192
	ds_read_b128 v[92:95], v74 offset:0
	ds_read_b128 v[96:99], v74 offset:8192
	ds_read_b128 v[100:103], v74 offset:16384
	ds_read_b128 v[104:107], v74 offset:24576
	ds_read_b128 v[108:111], v71 offset:0
	ds_read_b128 v[112:115], v71 offset:8192
	ds_read_b128 v[116:119], v75 offset:0
	ds_read_b128 v[120:123], v75 offset:8192
	ds_read_b128 v[124:127], v75 offset:16384
	ds_read_b128 v[128:131], v75 offset:24576
	s_waitcnt lgkmcnt(6)
	v_mfma_f32_16x16x32_bf16 v[16:19], v[92:95], v[84:87], 0
	v_mfma_f32_16x16x32_bf16 v[20:23], v[96:99], v[84:87], 0
	v_mfma_f32_16x16x32_bf16 v[24:27], v[100:103], v[84:87], 0
	v_mfma_f32_16x16x32_bf16 v[28:31], v[104:107], v[84:87], 0
	v_mfma_f32_16x16x32_bf16 v[48:51], v[92:95], v[88:91], 0
	v_mfma_f32_16x16x32_bf16 v[52:55], v[96:99], v[88:91], 0
	v_mfma_f32_16x16x32_bf16 v[56:59], v[100:103], v[88:91], 0
	v_mfma_f32_16x16x32_bf16 v[60:63], v[104:107], v[88:91], 0
	ds_read_b128 v[84:87], v72 offset:0
	ds_read_b128 v[88:91], v72 offset:8192
	ds_read_b128 v[92:95], v76 offset:0
	ds_read_b128 v[96:99], v76 offset:8192
	ds_read_b128 v[100:103], v76 offset:16384
	ds_read_b128 v[104:107], v76 offset:24576
	s_waitcnt lgkmcnt(6)
	v_mfma_f32_16x16x32_bf16 v[16:19], v[116:119], v[108:111], v[16:19]
	v_mfma_f32_16x16x32_bf16 v[20:23], v[120:123], v[108:111], v[20:23]
	v_mfma_f32_16x16x32_bf16 v[24:27], v[124:127], v[108:111], v[24:27]
	v_mfma_f32_16x16x32_bf16 v[28:31], v[128:131], v[108:111], v[28:31]
	v_mfma_f32_16x16x32_bf16 v[48:51], v[116:119], v[112:115], v[48:51]
	v_mfma_f32_16x16x32_bf16 v[52:55], v[120:123], v[112:115], v[52:55]
	v_mfma_f32_16x16x32_bf16 v[56:59], v[124:127], v[112:115], v[56:59]
	v_mfma_f32_16x16x32_bf16 v[60:63], v[128:131], v[112:115], v[60:63]
	ds_read_b128 v[108:111], v73 offset:0
	ds_read_b128 v[112:115], v73 offset:8192
	ds_read_b128 v[116:119], v77 offset:0
	ds_read_b128 v[120:123], v77 offset:8192
	ds_read_b128 v[124:127], v77 offset:16384
	ds_read_b128 v[128:131], v77 offset:24576
	s_waitcnt lgkmcnt(6)
	v_mfma_f32_16x16x32_bf16 v[16:19], v[92:95], v[84:87], v[16:19]
	v_mfma_f32_16x16x32_bf16 v[20:23], v[96:99], v[84:87], v[20:23]
	v_mfma_f32_16x16x32_bf16 v[24:27], v[100:103], v[84:87], v[24:27]
	v_mfma_f32_16x16x32_bf16 v[28:31], v[104:107], v[84:87], v[28:31]
	v_mfma_f32_16x16x32_bf16 v[48:51], v[92:95], v[88:91], v[48:51]
	v_mfma_f32_16x16x32_bf16 v[52:55], v[96:99], v[88:91], v[52:55]
	v_mfma_f32_16x16x32_bf16 v[56:59], v[100:103], v[88:91], v[56:59]
	v_mfma_f32_16x16x32_bf16 v[60:63], v[104:107], v[88:91], v[60:63]
	ds_read_b128 v[84:87], v70 offset:256
	ds_read_b128 v[88:91], v70 offset:8448
	ds_read_b128 v[92:95], v74 offset:256
	ds_read_b128 v[96:99], v74 offset:8448
	ds_read_b128 v[100:103], v74 offset:16640
	ds_read_b128 v[104:107], v74 offset:24832
	s_waitcnt lgkmcnt(6)
	v_mfma_f32_16x16x32_bf16 v[16:19], v[116:119], v[108:111], v[16:19]
	v_mfma_f32_16x16x32_bf16 v[20:23], v[120:123], v[108:111], v[20:23]
	v_mfma_f32_16x16x32_bf16 v[24:27], v[124:127], v[108:111], v[24:27]
	v_mfma_f32_16x16x32_bf16 v[28:31], v[128:131], v[108:111], v[28:31]
	v_mfma_f32_16x16x32_bf16 v[48:51], v[116:119], v[112:115], v[48:51]
	v_mfma_f32_16x16x32_bf16 v[52:55], v[120:123], v[112:115], v[52:55]
	v_mfma_f32_16x16x32_bf16 v[56:59], v[124:127], v[112:115], v[56:59]
	v_mfma_f32_16x16x32_bf16 v[60:63], v[128:131], v[112:115], v[60:63]
	ds_read_b128 v[108:111], v71 offset:256
	ds_read_b128 v[112:115], v71 offset:8448
	ds_read_b128 v[116:119], v75 offset:256
	ds_read_b128 v[120:123], v75 offset:8448
	ds_read_b128 v[124:127], v75 offset:16640
	ds_read_b128 v[128:131], v75 offset:24832
	s_waitcnt lgkmcnt(6)
	v_mfma_f32_16x16x32_bf16 v[16:19], v[92:95], v[84:87], v[16:19]
	v_mfma_f32_16x16x32_bf16 v[20:23], v[96:99], v[84:87], v[20:23]
	v_mfma_f32_16x16x32_bf16 v[24:27], v[100:103], v[84:87], v[24:27]
	v_mfma_f32_16x16x32_bf16 v[28:31], v[104:107], v[84:87], v[28:31]
	v_mfma_f32_16x16x32_bf16 v[48:51], v[92:95], v[88:91], v[48:51]
	v_mfma_f32_16x16x32_bf16 v[52:55], v[96:99], v[88:91], v[52:55]
	v_mfma_f32_16x16x32_bf16 v[56:59], v[100:103], v[88:91], v[56:59]
	v_mfma_f32_16x16x32_bf16 v[60:63], v[104:107], v[88:91], v[60:63]
	ds_read_b128 v[84:87], v72 offset:256
	ds_read_b128 v[88:91], v72 offset:8448
	ds_read_b128 v[92:95], v76 offset:256
	ds_read_b128 v[96:99], v76 offset:8448
	ds_read_b128 v[100:103], v76 offset:16640
	ds_read_b128 v[104:107], v76 offset:24832
	s_waitcnt lgkmcnt(6)
	v_mfma_f32_16x16x32_bf16 v[16:19], v[116:119], v[108:111], v[16:19]
	v_mfma_f32_16x16x32_bf16 v[20:23], v[120:123], v[108:111], v[20:23]
	v_mfma_f32_16x16x32_bf16 v[24:27], v[124:127], v[108:111], v[24:27]
	v_mfma_f32_16x16x32_bf16 v[28:31], v[128:131], v[108:111], v[28:31]
	v_mfma_f32_16x16x32_bf16 v[48:51], v[116:119], v[112:115], v[48:51]
	v_mfma_f32_16x16x32_bf16 v[52:55], v[120:123], v[112:115], v[52:55]
	v_mfma_f32_16x16x32_bf16 v[56:59], v[124:127], v[112:115], v[56:59]
	v_mfma_f32_16x16x32_bf16 v[60:63], v[128:131], v[112:115], v[60:63]
	ds_read_b128 v[108:111], v73 offset:256
	ds_read_b128 v[112:115], v73 offset:8448
	ds_read_b128 v[116:119], v77 offset:256
	ds_read_b128 v[120:123], v77 offset:8448
	ds_read_b128 v[124:127], v77 offset:16640
	ds_read_b128 v[128:131], v77 offset:24832
	s_waitcnt lgkmcnt(6)
	v_mfma_f32_16x16x32_bf16 v[16:19], v[92:95], v[84:87], v[16:19]
	v_mfma_f32_16x16x32_bf16 v[20:23], v[96:99], v[84:87], v[20:23]
	v_mfma_f32_16x16x32_bf16 v[24:27], v[100:103], v[84:87], v[24:27]
	v_mfma_f32_16x16x32_bf16 v[28:31], v[104:107], v[84:87], v[28:31]
	v_mfma_f32_16x16x32_bf16 v[48:51], v[92:95], v[88:91], v[48:51]
	v_mfma_f32_16x16x32_bf16 v[52:55], v[96:99], v[88:91], v[52:55]
	v_mfma_f32_16x16x32_bf16 v[56:59], v[100:103], v[88:91], v[56:59]
	v_mfma_f32_16x16x32_bf16 v[60:63], v[104:107], v[88:91], v[60:63]
	s_waitcnt lgkmcnt(0)
	v_mfma_f32_16x16x32_bf16 v[16:19], v[116:119], v[108:111], v[16:19]
	v_mfma_f32_16x16x32_bf16 v[20:23], v[120:123], v[108:111], v[20:23]
	v_mfma_f32_16x16x32_bf16 v[24:27], v[124:127], v[108:111], v[24:27]
	v_mfma_f32_16x16x32_bf16 v[28:31], v[128:131], v[108:111], v[28:31]
	v_mfma_f32_16x16x32_bf16 v[48:51], v[116:119], v[112:115], v[48:51]
	v_mfma_f32_16x16x32_bf16 v[52:55], v[120:123], v[112:115], v[52:55]
	v_mfma_f32_16x16x32_bf16 v[56:59], v[124:127], v[112:115], v[56:59]
	v_mfma_f32_16x16x32_bf16 v[60:63], v[128:131], v[112:115], v[60:63]
	s_nop 7
	global_store_dwordx4 v69, v[0:3], s[40:41] offset:0
	global_store_dwordx4 v69, v[4:7], s[40:41] offset:64
	global_store_dwordx4 v69, v[8:11], s[40:41] offset:128
	global_store_dwordx4 v69, v[12:15], s[40:41] offset:192
	global_store_dwordx4 v69, v[16:19], s[40:41] offset:512
	global_store_dwordx4 v69, v[20:23], s[40:41] offset:576
	global_store_dwordx4 v69, v[24:27], s[40:41] offset:640
	global_store_dwordx4 v69, v[28:31], s[40:41] offset:704
	global_store_dwordx4 v69, v[32:35], s[42:43] offset:0
	global_store_dwordx4 v69, v[36:39], s[42:43] offset:64
	global_store_dwordx4 v69, v[40:43], s[42:43] offset:128
	global_store_dwordx4 v69, v[44:47], s[42:43] offset:192
	global_store_dwordx4 v69, v[48:51], s[42:43] offset:512
	global_store_dwordx4 v69, v[52:55], s[42:43] offset:576
	global_store_dwordx4 v69, v[56:59], s[42:43] offset:640
	global_store_dwordx4 v69, v[60:63], s[42:43] offset:704

.LBB0_2133:
	s_cmp_gt_i32 s2, 63
	v_readfirstlane_b32 s10, v231
	s_cbranch_scc1 .LBB0_2149
	v_and_b32_e32 v64, 63, v231
	v_and_b32_e32 v65, 15, v64
	v_bfe_u32 v66, v64, 4, 2
	v_readfirstlane_b32 s44, v230
	s_and_b32 s47, s2, 7
	s_lshr_b32 s58, s2, 3
	s_lshl_b32 s60, s58, 9
	s_nop 0
	s_and_b32 s45, s44, 3
	s_lshr_b32 s46, s44, 2
	v_and_b32_e32 v67, 3, v65
	v_xor_b32_e32 v67, v66, v67
	v_lshlrev_b32_e32 v67, 4, v67
	v_lshl_add_u32 v67, v65, 9, v67
	v_lshrrev_b32_e32 v69, 2, v65
	s_lshl_b32 s61, s45, 14
	s_lshl_b32 s62, s46, 15
	s_add_u32 s62, s62, 0x10000
	v_xor_b32_e32 v70, 0, v69
	v_lshl_add_u32 v70, v70, 6, v67
	v_add_u32_e32 v74, s62, v70
	v_add_u32_e32 v70, s61, v70
	v_xor_b32_e32 v71, 1, v69
	v_lshl_add_u32 v71, v71, 6, v67
	v_add_u32_e32 v75, s62, v71
	v_add_u32_e32 v71, s61, v71
	v_xor_b32_e32 v72, 2, v69
	v_lshl_add_u32 v72, v72, 6, v67
	v_add_u32_e32 v76, s62, v72
	v_add_u32_e32 v72, s61, v72
	v_xor_b32_e32 v73, 3, v69
	v_lshl_add_u32 v73, v73, 6, v67
	v_add_u32_e32 v77, s62, v73
	v_add_u32_e32 v73, s61, v73
	v_lshrrev_b32_e32 v68, 5, v64
	s_lshl_b32 s63, s44, 1
	v_add_u32_e32 v69, s63, v68
	v_and_b32_e32 v67, 31, v64
	v_xor_b32_e32 v67, v67, v69
	v_lshlrev_b32_e32 v67, 4, v67
	v_mul_u32_u24_e32 v68, 0x1000, v68
	v_add_u32_e32 v68, v68, v67
	v_lshlrev_b32_e32 v69, 13, v65
	v_lshl_add_u32 v69, v66, 4, v69
	s_lshl_b32 s59, s44, 1
	s_mul_i32 s59, s59, 0x1000
	s_add_u32 s36, s28, 0x19a00000
	s_addc_u32 s37, s29, 0
	s_add_u32 s36, s36, 0x2000000
	s_addc_u32 s37, s37, 0
	s_add_u32 s36, s36, s59
	s_addc_u32 s37, s37, 0
	s_add_u32 s36, s36, s60
	s_addc_u32 s37, s37, 0
	s_lshl_b32 s61, s47, 8
	s_mul_i32 s61, s61, 0x1000
	s_add_u32 s38, s28, 0x7800000
	s_addc_u32 s39, s29, 0
	s_add_u32 s38, s38, s61
	s_addc_u32 s39, s39, 0
	s_add_u32 s38, s38, s59
	s_addc_u32 s39, s39, 0
	s_add_u32 s38, s38, s60
	s_addc_u32 s39, s39, 0
	s_lshl_b32 s62, s58, 7
	s_lshl_b32 s63, s45, 5
	s_add_u32 s62, s62, s63
	s_lshl_b32 s62, s62, 13
	s_lshl_b32 s63, s47, 10
	s_lshl_b32 s3, s46, 8
	s_add_u32 s62, s62, s63
	s_add_u32 s62, s62, s3
	s_add_u32 s40, s28, 0x2ec00000
	s_addc_u32 s41, s29, 0
	s_add_u32 s40, s40, s62
	s_addc_u32 s41, s41, 0
	s_add_u32 s42, s40, 0x20000
	s_addc_u32 s43, s41, 0
	s_lshl_b32 s59, s44, 10
	s_mov_b64 s[10:11], s[36:37]
	s_add_u32 s12, s59, 0x0
	s_mov_b32 m0, s12
	s_add_u32 s12, s12, 0x2000
	global_load_lds_dwordx4 v68, s[10:11]
	s_add_u32 s10, s10, 0x10000
	s_addc_u32 s11, s11, 0
	s_mov_b32 m0, s12
	s_add_u32 s12, s12, 0x2000
	global_load_lds_dwordx4 v68, s[10:11]
	s_add_u32 s10, s10, 0x10000
	s_addc_u32 s11, s11, 0
	s_mov_b32 m0, s12
	s_add_u32 s12, s12, 0x2000
	global_load_lds_dwordx4 v68, s[10:11]
	s_add_u32 s10, s10, 0x10000
	s_addc_u32 s11, s11, 0
	s_mov_b32 m0, s12
	s_add_u32 s12, s12, 0x2000
	global_load_lds_dwordx4 v68, s[10:11]
	s_add_u32 s10, s10, 0x10000
	s_addc_u32 s11, s11, 0
	s_mov_b32 m0, s12
	s_add_u32 s12, s12, 0x2000
	global_load_lds_dwordx4 v68, s[10:11]
	s_add_u32 s10, s10, 0x10000
	s_addc_u32 s11, s11, 0
	s_mov_b32 m0, s12
	s_add_u32 s12, s12, 0x2000
	global_load_lds_dwordx4 v68, s[10:11]
	s_add_u32 s10, s10, 0x10000
	s_addc_u32 s11, s11, 0
	s_mov_b32 m0, s12
	s_add_u32 s12, s12, 0x2000
	global_load_lds_dwordx4 v68, s[10:11]
	s_add_u32 s10, s10, 0x10000
	s_addc_u32 s11, s11, 0
	s_mov_b32 m0, s12
	s_add_u32 s12, s12, 0x2000
	global_load_lds_dwordx4 v68, s[10:11]
	s_add_u32 s10, s10, 0x10000
	s_addc_u32 s11, s11, 0
	s_mov_b64 s[10:11], s[38:39]
	s_add_u32 s12, s59, 0x10000
	s_mov_b32 m0, s12
	s_add_u32 s12, s12, 0x2000
	global_load_lds_dwordx4 v68, s[10:11]
	s_add_u32 s10, s10, 0x10000
	s_addc_u32 s11, s11, 0
	s_mov_b32 m0, s12
	s_add_u32 s12, s12, 0x2000
	global_load_lds_dwordx4 v68, s[10:11]
	s_add_u32 s10, s10, 0x10000
	s_addc_u32 s11, s11, 0
	s_mov_b32 m0, s12
	s_add_u32 s12, s12, 0x2000
	global_load_lds_dwordx4 v68, s[10:11]
	s_add_u32 s10, s10, 0x10000
	s_addc_u32 s11, s11, 0
	s_mov_b32 m0, s12
	s_add_u32 s12, s12, 0x2000
	global_load_lds_dwordx4 v68, s[10:11]
	s_add_u32 s10, s10, 0x10000
	s_addc_u32 s11, s11, 0
	s_mov_b32 m0, s12
	s_add_u32 s12, s12, 0x2000
	global_load_lds_dwordx4 v68, s[10:11]
	s_add_u32 s10, s10, 0x10000
	s_addc_u32 s11, s11, 0
	s_mov_b32 m0, s12
	s_add_u32 s12, s12, 0x2000
	global_load_lds_dwordx4 v68, s[10:11]
	s_add_u32 s10, s10, 0x10000
	s_addc_u32 s11, s11, 0
	s_mov_b32 m0, s12
	s_add_u32 s12, s12, 0x2000
	global_load_lds_dwordx4 v68, s[10:11]
	s_add_u32 s10, s10, 0x10000
	s_addc_u32 s11, s11, 0
	s_mov_b32 m0, s12
	s_add_u32 s12, s12, 0x2000
	global_load_lds_dwordx4 v68, s[10:11]
	s_add_u32 s10, s10, 0x10000
	s_addc_u32 s11, s11, 0
	s_add_u32 s38, s38, 0x80000
	s_addc_u32 s39, s39, 0
	s_waitcnt vmcnt(0)
	s_barrier
	ds_read_b128 v[84:87], v70 offset:0
	ds_read_b128 v[88:91], v70 offset:8192
	ds_read_b128 v[92:95], v74 offset:0
	ds_read_b128 v[96:99], v74 offset:8192
	ds_read_b128 v[100:103], v74 offset:16384
	ds_read_b128 v[104:107], v74 offset:24576
	ds_read_b128 v[108:111], v71 offset:0
	ds_read_b128 v[112:115], v71 offset:8192
	ds_read_b128 v[116:119], v75 offset:0
	ds_read_b128 v[120:123], v75 offset:8192
	ds_read_b128 v[124:127], v75 offset:16384
	ds_read_b128 v[128:131], v75 offset:24576
	s_waitcnt lgkmcnt(6)
	v_mfma_f32_16x16x32_bf16 v[0:3], v[92:95], v[84:87], 0
	v_mfma_f32_16x16x32_bf16 v[4:7], v[96:99], v[84:87], 0
	v_mfma_f32_16x16x32_bf16 v[8:11], v[100:103], v[84:87], 0
	v_mfma_f32_16x16x32_bf16 v[12:15], v[104:107], v[84:87], 0
	v_mfma_f32_16x16x32_bf16 v[32:35], v[92:95], v[88:91], 0
	v_mfma_f32_16x16x32_bf16 v[36:39], v[96:99], v[88:91], 0
	v_mfma_f32_16x16x32_bf16 v[40:43], v[100:103], v[88:91], 0
	v_mfma_f32_16x16x32_bf16 v[44:47], v[104:107], v[88:91], 0
	ds_read_b128 v[84:87], v72 offset:0
	ds_read_b128 v[88:91], v72 offset:8192
	ds_read_b128 v[92:95], v76 offset:0
	ds_read_b128 v[96:99], v76 offset:8192
	ds_read_b128 v[100:103], v76 offset:16384
	ds_read_b128 v[104:107], v76 offset:24576
	s_waitcnt lgkmcnt(6)
	v_mfma_f32_16x16x32_bf16 v[0:3], v[116:119], v[108:111], v[0:3]
	v_mfma_f32_16x16x32_bf16 v[4:7], v[120:123], v[108:111], v[4:7]
	v_mfma_f32_16x16x32_bf16 v[8:11], v[124:127], v[108:111], v[8:11]
	v_mfma_f32_16x16x32_bf16 v[12:15], v[128:131], v[108:111], v[12:15]
	v_mfma_f32_16x16x32_bf16 v[32:35], v[116:119], v[112:115], v[32:35]
	v_mfma_f32_16x16x32_bf16 v[36:39], v[120:123], v[112:115], v[36:39]
	v_mfma_f32_16x16x32_bf16 v[40:43], v[124:127], v[112:115], v[40:43]
	v_mfma_f32_16x16x32_bf16 v[44:47], v[128:131], v[112:115], v[44:47]
	ds_read_b128 v[108:111], v73 offset:0
	ds_read_b128 v[112:115], v73 offset:8192
	ds_read_b128 v[116:119], v77 offset:0
	ds_read_b128 v[120:123], v77 offset:8192
	ds_read_b128 v[124:127], v77 offset:16384
	ds_read_b128 v[128:131], v77 offset:24576
	s_waitcnt lgkmcnt(6)
	v_mfma_f32_16x16x32_bf16 v[0:3], v[92:95], v[84:87], v[0:3]
	v_mfma_f32_16x16x32_bf16 v[4:7], v[96:99], v[84:87], v[4:7]
	v_mfma_f32_16x16x32_bf16 v[8:11], v[100:103], v[84:87], v[8:11]
	v_mfma_f32_16x16x32_bf16 v[12:15], v[104:107], v[84:87], v[12:15]
	v_mfma_f32_16x16x32_bf16 v[32:35], v[92:95], v[88:91], v[32:35]
	v_mfma_f32_16x16x32_bf16 v[36:39], v[96:99], v[88:91], v[36:39]
	v_mfma_f32_16x16x32_bf16 v[40:43], v[100:103], v[88:91], v[40:43]
	v_mfma_f32_16x16x32_bf16 v[44:47], v[104:107], v[88:91], v[44:47]
	ds_read_b128 v[84:87], v70 offset:256
	ds_read_b128 v[88:91], v70 offset:8448
	ds_read_b128 v[92:95], v74 offset:256
	ds_read_b128 v[96:99], v74 offset:8448
	ds_read_b128 v[100:103], v74 offset:16640
	ds_read_b128 v[104:107], v74 offset:24832
	s_waitcnt lgkmcnt(6)
	v_mfma_f32_16x16x32_bf16 v[0:3], v[116:119], v[108:111], v[0:3]
	v_mfma_f32_16x16x32_bf16 v[4:7], v[120:123], v[108:111], v[4:7]
	v_mfma_f32_16x16x32_bf16 v[8:11], v[124:127], v[108:111], v[8:11]
	v_mfma_f32_16x16x32_bf16 v[12:15], v[128:131], v[108:111], v[12:15]
	v_mfma_f32_16x16x32_bf16 v[32:35], v[116:119], v[112:115], v[32:35]
	v_mfma_f32_16x16x32_bf16 v[36:39], v[120:123], v[112:115], v[36:39]
	v_mfma_f32_16x16x32_bf16 v[40:43], v[124:127], v[112:115], v[40:43]
	v_mfma_f32_16x16x32_bf16 v[44:47], v[128:131], v[112:115], v[44:47]
	ds_read_b128 v[108:111], v71 offset:256
	ds_read_b128 v[112:115], v71 offset:8448
	ds_read_b128 v[116:119], v75 offset:256
	ds_read_b128 v[120:123], v75 offset:8448
	ds_read_b128 v[124:127], v75 offset:16640
	ds_read_b128 v[128:131], v75 offset:24832
	s_waitcnt lgkmcnt(6)
	v_mfma_f32_16x16x32_bf16 v[0:3], v[92:95], v[84:87], v[0:3]
	v_mfma_f32_16x16x32_bf16 v[4:7], v[96:99], v[84:87], v[4:7]
	v_mfma_f32_16x16x32_bf16 v[8:11], v[100:103], v[84:87], v[8:11]
	v_mfma_f32_16x16x32_bf16 v[12:15], v[104:107], v[84:87], v[12:15]
	v_mfma_f32_16x16x32_bf16 v[32:35], v[92:95], v[88:91], v[32:35]
	v_mfma_f32_16x16x32_bf16 v[36:39], v[96:99], v[88:91], v[36:39]
	v_mfma_f32_16x16x32_bf16 v[40:43], v[100:103], v[88:91], v[40:43]
	v_mfma_f32_16x16x32_bf16 v[44:47], v[104:107], v[88:91], v[44:47]
	ds_read_b128 v[84:87], v72 offset:256
	ds_read_b128 v[88:91], v72 offset:8448
	ds_read_b128 v[92:95], v76 offset:256
	ds_read_b128 v[96:99], v76 offset:8448
	ds_read_b128 v[100:103], v76 offset:16640
	ds_read_b128 v[104:107], v76 offset:24832
	s_waitcnt lgkmcnt(6)
	v_mfma_f32_16x16x32_bf16 v[0:3], v[116:119], v[108:111], v[0:3]
	v_mfma_f32_16x16x32_bf16 v[4:7], v[120:123], v[108:111], v[4:7]
	v_mfma_f32_16x16x32_bf16 v[8:11], v[124:127], v[108:111], v[8:11]
	v_mfma_f32_16x16x32_bf16 v[12:15], v[128:131], v[108:111], v[12:15]
	v_mfma_f32_16x16x32_bf16 v[32:35], v[116:119], v[112:115], v[32:35]
	v_mfma_f32_16x16x32_bf16 v[36:39], v[120:123], v[112:115], v[36:39]
	v_mfma_f32_16x16x32_bf16 v[40:43], v[124:127], v[112:115], v[40:43]
	v_mfma_f32_16x16x32_bf16 v[44:47], v[128:131], v[112:115], v[44:47]
	ds_read_b128 v[108:111], v73 offset:256
	ds_read_b128 v[112:115], v73 offset:8448
	ds_read_b128 v[116:119], v77 offset:256
	ds_read_b128 v[120:123], v77 offset:8448
	ds_read_b128 v[124:127], v77 offset:16640
	ds_read_b128 v[128:131], v77 offset:24832
	s_waitcnt lgkmcnt(6)
	v_mfma_f32_16x16x32_bf16 v[0:3], v[92:95], v[84:87], v[0:3]
	v_mfma_f32_16x16x32_bf16 v[4:7], v[96:99], v[84:87], v[4:7]
	v_mfma_f32_16x16x32_bf16 v[8:11], v[100:103], v[84:87], v[8:11]
	v_mfma_f32_16x16x32_bf16 v[12:15], v[104:107], v[84:87], v[12:15]
	v_mfma_f32_16x16x32_bf16 v[32:35], v[92:95], v[88:91], v[32:35]
	v_mfma_f32_16x16x32_bf16 v[36:39], v[96:99], v[88:91], v[36:39]
	v_mfma_f32_16x16x32_bf16 v[40:43], v[100:103], v[88:91], v[40:43]
	v_mfma_f32_16x16x32_bf16 v[44:47], v[104:107], v[88:91], v[44:47]
	s_waitcnt lgkmcnt(0)
	v_mfma_f32_16x16x32_bf16 v[0:3], v[116:119], v[108:111], v[0:3]
	v_mfma_f32_16x16x32_bf16 v[4:7], v[120:123], v[108:111], v[4:7]
	v_mfma_f32_16x16x32_bf16 v[8:11], v[124:127], v[108:111], v[8:11]
	v_mfma_f32_16x16x32_bf16 v[12:15], v[128:131], v[108:111], v[12:15]
	v_mfma_f32_16x16x32_bf16 v[32:35], v[116:119], v[112:115], v[32:35]
	v_mfma_f32_16x16x32_bf16 v[36:39], v[120:123], v[112:115], v[36:39]
	v_mfma_f32_16x16x32_bf16 v[40:43], v[124:127], v[112:115], v[40:43]
	v_mfma_f32_16x16x32_bf16 v[44:47], v[128:131], v[112:115], v[44:47]
	s_barrier
	s_mov_b64 s[10:11], s[38:39]
	s_add_u32 s12, s59, 0x10000
	s_mov_b32 m0, s12
	s_add_u32 s12, s12, 0x2000
	global_load_lds_dwordx4 v68, s[10:11]
	s_add_u32 s10, s10, 0x10000
	s_addc_u32 s11, s11, 0
	s_mov_b32 m0, s12
	s_add_u32 s12, s12, 0x2000
	global_load_lds_dwordx4 v68, s[10:11]
	s_add_u32 s10, s10, 0x10000
	s_addc_u32 s11, s11, 0
	s_mov_b32 m0, s12
	s_add_u32 s12, s12, 0x2000
	global_load_lds_dwordx4 v68, s[10:11]
	s_add_u32 s10, s10, 0x10000
	s_addc_u32 s11, s11, 0
	s_mov_b32 m0, s12
	s_add_u32 s12, s12, 0x2000
	global_load_lds_dwordx4 v68, s[10:11]
	s_add_u32 s10, s10, 0x10000
	s_addc_u32 s11, s11, 0
	s_mov_b32 m0, s12
	s_add_u32 s12, s12, 0x2000
	global_load_lds_dwordx4 v68, s[10:11]
	s_add_u32 s10, s10, 0x10000
	s_addc_u32 s11, s11, 0
	s_mov_b32 m0, s12
	s_add_u32 s12, s12, 0x2000
	global_load_lds_dwordx4 v68, s[10:11]
	s_add_u32 s10, s10, 0x10000
	s_addc_u32 s11, s11, 0
	s_mov_b32 m0, s12
	s_add_u32 s12, s12, 0x2000
	global_load_lds_dwordx4 v68, s[10:11]
	s_add_u32 s10, s10, 0x10000
	s_addc_u32 s11, s11, 0
	s_mov_b32 m0, s12
	s_add_u32 s12, s12, 0x2000
	global_load_lds_dwordx4 v68, s[10:11]
	s_add_u32 s10, s10, 0x10000
	s_addc_u32 s11, s11, 0
	s_waitcnt vmcnt(0)
	s_barrier
	ds_read_b128 v[84:87], v70 offset:0
	ds_read_b128 v[88:91], v70 offset:8192
	ds_read_b128 v[92:95], v74 offset:0
	ds_read_b128 v[96:99], v74 offset:8192
	ds_read_b128 v[100:103], v74 offset:16384
	ds_read_b128 v[104:107], v74 offset:24576
	ds_read_b128 v[108:111], v71 offset:0
	ds_read_b128 v[112:115], v71 offset:8192
	ds_read_b128 v[116:119], v75 offset:0
	ds_read_b128 v[120:123], v75 offset:8192
	ds_read_b128 v[124:127], v75 offset:16384
	ds_read_b128 v[128:131], v75 offset:24576
	s_waitcnt lgkmcnt(6)
	v_mfma_f32_16x16x32_bf16 v[16:19], v[92:95], v[84:87], 0
	v_mfma_f32_16x16x32_bf16 v[20:23], v[96:99], v[84:87], 0
	v_mfma_f32_16x16x32_bf16 v[24:27], v[100:103], v[84:87], 0
	v_mfma_f32_16x16x32_bf16 v[28:31], v[104:107], v[84:87], 0
	v_mfma_f32_16x16x32_bf16 v[48:51], v[92:95], v[88:91], 0
	v_mfma_f32_16x16x32_bf16 v[52:55], v[96:99], v[88:91], 0
	v_mfma_f32_16x16x32_bf16 v[56:59], v[100:103], v[88:91], 0
	v_mfma_f32_16x16x32_bf16 v[60:63], v[104:107], v[88:91], 0
	ds_read_b128 v[84:87], v72 offset:0
	ds_read_b128 v[88:91], v72 offset:8192
	ds_read_b128 v[92:95], v76 offset:0
	ds_read_b128 v[96:99], v76 offset:8192
	ds_read_b128 v[100:103], v76 offset:16384
	ds_read_b128 v[104:107], v76 offset:24576
	s_waitcnt lgkmcnt(6)
	v_mfma_f32_16x16x32_bf16 v[16:19], v[116:119], v[108:111], v[16:19]
	v_mfma_f32_16x16x32_bf16 v[20:23], v[120:123], v[108:111], v[20:23]
	v_mfma_f32_16x16x32_bf16 v[24:27], v[124:127], v[108:111], v[24:27]
	v_mfma_f32_16x16x32_bf16 v[28:31], v[128:131], v[108:111], v[28:31]
	v_mfma_f32_16x16x32_bf16 v[48:51], v[116:119], v[112:115], v[48:51]
	v_mfma_f32_16x16x32_bf16 v[52:55], v[120:123], v[112:115], v[52:55]
	v_mfma_f32_16x16x32_bf16 v[56:59], v[124:127], v[112:115], v[56:59]
	v_mfma_f32_16x16x32_bf16 v[60:63], v[128:131], v[112:115], v[60:63]
	ds_read_b128 v[108:111], v73 offset:0
	ds_read_b128 v[112:115], v73 offset:8192
	ds_read_b128 v[116:119], v77 offset:0
	ds_read_b128 v[120:123], v77 offset:8192
	ds_read_b128 v[124:127], v77 offset:16384
	ds_read_b128 v[128:131], v77 offset:24576
	s_waitcnt lgkmcnt(6)
	v_mfma_f32_16x16x32_bf16 v[16:19], v[92:95], v[84:87], v[16:19]
	v_mfma_f32_16x16x32_bf16 v[20:23], v[96:99], v[84:87], v[20:23]
	v_mfma_f32_16x16x32_bf16 v[24:27], v[100:103], v[84:87], v[24:27]
	v_mfma_f32_16x16x32_bf16 v[28:31], v[104:107], v[84:87], v[28:31]
	v_mfma_f32_16x16x32_bf16 v[48:51], v[92:95], v[88:91], v[48:51]
	v_mfma_f32_16x16x32_bf16 v[52:55], v[96:99], v[88:91], v[52:55]
	v_mfma_f32_16x16x32_bf16 v[56:59], v[100:103], v[88:91], v[56:59]
	v_mfma_f32_16x16x32_bf16 v[60:63], v[104:107], v[88:91], v[60:63]
	ds_read_b128 v[84:87], v70 offset:256
	ds_read_b128 v[88:91], v70 offset:8448
	ds_read_b128 v[92:95], v74 offset:256
	ds_read_b128 v[96:99], v74 offset:8448
	ds_read_b128 v[100:103], v74 offset:16640
	ds_read_b128 v[104:107], v74 offset:24832
	s_waitcnt lgkmcnt(6)
	v_mfma_f32_16x16x32_bf16 v[16:19], v[116:119], v[108:111], v[16:19]
	v_mfma_f32_16x16x32_bf16 v[20:23], v[120:123], v[108:111], v[20:23]
	v_mfma_f32_16x16x32_bf16 v[24:27], v[124:127], v[108:111], v[24:27]
	v_mfma_f32_16x16x32_bf16 v[28:31], v[128:131], v[108:111], v[28:31]
	v_mfma_f32_16x16x32_bf16 v[48:51], v[116:119], v[112:115], v[48:51]
	v_mfma_f32_16x16x32_bf16 v[52:55], v[120:123], v[112:115], v[52:55]
	v_mfma_f32_16x16x32_bf16 v[56:59], v[124:127], v[112:115], v[56:59]
	v_mfma_f32_16x16x32_bf16 v[60:63], v[128:131], v[112:115], v[60:63]
	ds_read_b128 v[108:111], v71 offset:256
	ds_read_b128 v[112:115], v71 offset:8448
	ds_read_b128 v[116:119], v75 offset:256
	ds_read_b128 v[120:123], v75 offset:8448
	ds_read_b128 v[124:127], v75 offset:16640
	ds_read_b128 v[128:131], v75 offset:24832
	s_waitcnt lgkmcnt(6)
	v_mfma_f32_16x16x32_bf16 v[16:19], v[92:95], v[84:87], v[16:19]
	v_mfma_f32_16x16x32_bf16 v[20:23], v[96:99], v[84:87], v[20:23]
	v_mfma_f32_16x16x32_bf16 v[24:27], v[100:103], v[84:87], v[24:27]
	v_mfma_f32_16x16x32_bf16 v[28:31], v[104:107], v[84:87], v[28:31]
	v_mfma_f32_16x16x32_bf16 v[48:51], v[92:95], v[88:91], v[48:51]
	v_mfma_f32_16x16x32_bf16 v[52:55], v[96:99], v[88:91], v[52:55]
	v_mfma_f32_16x16x32_bf16 v[56:59], v[100:103], v[88:91], v[56:59]
	v_mfma_f32_16x16x32_bf16 v[60:63], v[104:107], v[88:91], v[60:63]
	ds_read_b128 v[84:87], v72 offset:256
	ds_read_b128 v[88:91], v72 offset:8448
	ds_read_b128 v[92:95], v76 offset:256
	ds_read_b128 v[96:99], v76 offset:8448
	ds_read_b128 v[100:103], v76 offset:16640
	ds_read_b128 v[104:107], v76 offset:24832
	s_waitcnt lgkmcnt(6)
	v_mfma_f32_16x16x32_bf16 v[16:19], v[116:119], v[108:111], v[16:19]
	v_mfma_f32_16x16x32_bf16 v[20:23], v[120:123], v[108:111], v[20:23]
	v_mfma_f32_16x16x32_bf16 v[24:27], v[124:127], v[108:111], v[24:27]
	v_mfma_f32_16x16x32_bf16 v[28:31], v[128:131], v[108:111], v[28:31]
	v_mfma_f32_16x16x32_bf16 v[48:51], v[116:119], v[112:115], v[48:51]
	v_mfma_f32_16x16x32_bf16 v[52:55], v[120:123], v[112:115], v[52:55]
	v_mfma_f32_16x16x32_bf16 v[56:59], v[124:127], v[112:115], v[56:59]
	v_mfma_f32_16x16x32_bf16 v[60:63], v[128:131], v[112:115], v[60:63]
	ds_read_b128 v[108:111], v73 offset:256
	ds_read_b128 v[112:115], v73 offset:8448
	ds_read_b128 v[116:119], v77 offset:256
	ds_read_b128 v[120:123], v77 offset:8448
	ds_read_b128 v[124:127], v77 offset:16640
	ds_read_b128 v[128:131], v77 offset:24832
	s_waitcnt lgkmcnt(6)
	v_mfma_f32_16x16x32_bf16 v[16:19], v[92:95], v[84:87], v[16:19]
	v_mfma_f32_16x16x32_bf16 v[20:23], v[96:99], v[84:87], v[20:23]
	v_mfma_f32_16x16x32_bf16 v[24:27], v[100:103], v[84:87], v[24:27]
	v_mfma_f32_16x16x32_bf16 v[28:31], v[104:107], v[84:87], v[28:31]
	v_mfma_f32_16x16x32_bf16 v[48:51], v[92:95], v[88:91], v[48:51]
	v_mfma_f32_16x16x32_bf16 v[52:55], v[96:99], v[88:91], v[52:55]
	v_mfma_f32_16x16x32_bf16 v[56:59], v[100:103], v[88:91], v[56:59]
	v_mfma_f32_16x16x32_bf16 v[60:63], v[104:107], v[88:91], v[60:63]
	s_waitcnt lgkmcnt(0)
	v_mfma_f32_16x16x32_bf16 v[16:19], v[116:119], v[108:111], v[16:19]
	v_mfma_f32_16x16x32_bf16 v[20:23], v[120:123], v[108:111], v[20:23]
	v_mfma_f32_16x16x32_bf16 v[24:27], v[124:127], v[108:111], v[24:27]
	v_mfma_f32_16x16x32_bf16 v[28:31], v[128:131], v[108:111], v[28:31]
	v_mfma_f32_16x16x32_bf16 v[48:51], v[116:119], v[112:115], v[48:51]
	v_mfma_f32_16x16x32_bf16 v[52:55], v[120:123], v[112:115], v[52:55]
	v_mfma_f32_16x16x32_bf16 v[56:59], v[124:127], v[112:115], v[56:59]
	v_mfma_f32_16x16x32_bf16 v[60:63], v[128:131], v[112:115], v[60:63]
	s_nop 7
	global_store_dwordx4 v69, v[0:3], s[40:41] offset:0
	global_store_dwordx4 v69, v[4:7], s[40:41] offset:64
	global_store_dwordx4 v69, v[8:11], s[40:41] offset:128
	global_store_dwordx4 v69, v[12:15], s[40:41] offset:192
	global_store_dwordx4 v69, v[16:19], s[40:41] offset:512
	global_store_dwordx4 v69, v[20:23], s[40:41] offset:576
	global_store_dwordx4 v69, v[24:27], s[40:41] offset:640
	global_store_dwordx4 v69, v[28:31], s[40:41] offset:704
	global_store_dwordx4 v69, v[32:35], s[42:43] offset:0
	global_store_dwordx4 v69, v[36:39], s[42:43] offset:64
	global_store_dwordx4 v69, v[40:43], s[42:43] offset:128
	global_store_dwordx4 v69, v[44:47], s[42:43] offset:192
	global_store_dwordx4 v69, v[48:51], s[42:43] offset:512
	global_store_dwordx4 v69, v[52:55], s[42:43] offset:576
	global_store_dwordx4 v69, v[56:59], s[42:43] offset:640
	global_store_dwordx4 v69, v[60:63], s[42:43] offset:704

.LBB0_2383:
	s_cmpk_gt_i32 s2, 0xaf
	v_readfirstlane_b32 s7, v231
	s_cbranch_scc1 .LBB0_2399
	v_and_b32_e32 v64, 63, v231
	v_and_b32_e32 v65, 15, v64
	v_bfe_u32 v66, v64, 4, 2
	v_readfirstlane_b32 s44, v230
	s_and_b32 s47, s2, 7
	s_lshr_b32 s58, s2, 3
	s_lshl_b32 s60, s58, 9
	s_nop 0
	s_and_b32 s45, s44, 3
	s_lshr_b32 s46, s44, 2
	v_and_b32_e32 v67, 3, v65
	v_xor_b32_e32 v67, v66, v67
	v_lshlrev_b32_e32 v67, 4, v67
	v_lshl_add_u32 v67, v65, 9, v67
	v_lshrrev_b32_e32 v69, 2, v65
	s_lshl_b32 s61, s45, 14
	s_lshl_b32 s62, s46, 15
	s_add_u32 s62, s62, 0x10000
	v_xor_b32_e32 v70, 0, v69
	v_lshl_add_u32 v70, v70, 6, v67
	v_add_u32_e32 v74, s62, v70
	v_add_u32_e32 v70, s61, v70
	v_xor_b32_e32 v71, 1, v69
	v_lshl_add_u32 v71, v71, 6, v67
	v_add_u32_e32 v75, s62, v71
	v_add_u32_e32 v71, s61, v71
	v_xor_b32_e32 v72, 2, v69
	v_lshl_add_u32 v72, v72, 6, v67
	v_add_u32_e32 v76, s62, v72
	v_add_u32_e32 v72, s61, v72
	v_xor_b32_e32 v73, 3, v69
	v_lshl_add_u32 v73, v73, 6, v67
	v_add_u32_e32 v77, s62, v73
	v_add_u32_e32 v73, s61, v73
	v_lshrrev_b32_e32 v68, 5, v64
	s_lshl_b32 s63, s44, 1
	v_add_u32_e32 v69, s63, v68
	v_and_b32_e32 v67, 31, v64
	v_xor_b32_e32 v67, v67, v69
	v_lshlrev_b32_e32 v67, 4, v67
	v_mul_u32_u24_e32 v68, 0x2c00, v68
	v_add_u32_e32 v68, v68, v67
	v_lshlrev_b32_e32 v69, 13, v65
	v_lshl_add_u32 v69, v66, 4, v69
	s_lshl_b32 s59, s44, 1
	s_mul_i32 s59, s59, 0x2c00
	s_add_u32 s36, s28, 0x1d300000
	s_addc_u32 s37, s29, 0
	s_add_u32 s36, s36, 0x5800000
	s_addc_u32 s37, s37, 0
	s_add_u32 s36, s36, s59
	s_addc_u32 s37, s37, 0
	s_add_u32 s36, s36, s60
	s_addc_u32 s37, s37, 0
	s_lshl_b32 s61, s47, 8
	s_mul_i32 s61, s61, 0x2c00
	s_add_u32 s38, s28, 0xac00000
	s_addc_u32 s39, s29, 0
	s_add_u32 s38, s38, s61
	s_addc_u32 s39, s39, 0
	s_add_u32 s38, s38, s59
	s_addc_u32 s39, s39, 0
	s_add_u32 s38, s38, s60
	s_addc_u32 s39, s39, 0
	s_lshl_b32 s62, s58, 7
	s_lshl_b32 s63, s45, 5
	s_add_u32 s62, s62, s63
	s_lshl_b32 s62, s62, 13
	s_lshl_b32 s63, s47, 10
	s_lshl_b32 s3, s46, 8
	s_add_u32 s62, s62, s63
	s_add_u32 s62, s62, s3
	s_add_u32 s40, s28, 0x2ec00000
	s_addc_u32 s41, s29, 0
	s_add_u32 s40, s40, s62
	s_addc_u32 s41, s41, 0
	s_add_u32 s42, s40, 0x20000
	s_addc_u32 s43, s41, 0
	s_lshl_b32 s59, s44, 10
	s_mov_b64 s[10:11], s[36:37]
	s_add_u32 s12, s59, 0x0
	s_mov_b32 m0, s12
	s_add_u32 s12, s12, 0x2000
	global_load_lds_dwordx4 v68, s[10:11]
	s_add_u32 s10, s10, 0x2c000
	s_addc_u32 s11, s11, 0
	s_mov_b32 m0, s12
	s_add_u32 s12, s12, 0x2000
	global_load_lds_dwordx4 v68, s[10:11]
	s_add_u32 s10, s10, 0x2c000
	s_addc_u32 s11, s11, 0
	s_mov_b32 m0, s12
	s_add_u32 s12, s12, 0x2000
	global_load_lds_dwordx4 v68, s[10:11]
	s_add_u32 s10, s10, 0x2c000
	s_addc_u32 s11, s11, 0
	s_mov_b32 m0, s12
	s_add_u32 s12, s12, 0x2000
	global_load_lds_dwordx4 v68, s[10:11]
	s_add_u32 s10, s10, 0x2c000
	s_addc_u32 s11, s11, 0
	s_mov_b32 m0, s12
	s_add_u32 s12, s12, 0x2000
	global_load_lds_dwordx4 v68, s[10:11]
	s_add_u32 s10, s10, 0x2c000
	s_addc_u32 s11, s11, 0
	s_mov_b32 m0, s12
	s_add_u32 s12, s12, 0x2000
	global_load_lds_dwordx4 v68, s[10:11]
	s_add_u32 s10, s10, 0x2c000
	s_addc_u32 s11, s11, 0
	s_mov_b32 m0, s12
	s_add_u32 s12, s12, 0x2000
	global_load_lds_dwordx4 v68, s[10:11]
	s_add_u32 s10, s10, 0x2c000
	s_addc_u32 s11, s11, 0
	s_mov_b32 m0, s12
	s_add_u32 s12, s12, 0x2000
	global_load_lds_dwordx4 v68, s[10:11]
	s_add_u32 s10, s10, 0x2c000
	s_addc_u32 s11, s11, 0
	s_mov_b64 s[10:11], s[38:39]
	s_add_u32 s12, s59, 0x10000
	s_mov_b32 m0, s12
	s_add_u32 s12, s12, 0x2000
	global_load_lds_dwordx4 v68, s[10:11]
	s_add_u32 s10, s10, 0x2c000
	s_addc_u32 s11, s11, 0
	s_mov_b32 m0, s12
	s_add_u32 s12, s12, 0x2000
	global_load_lds_dwordx4 v68, s[10:11]
	s_add_u32 s10, s10, 0x2c000
	s_addc_u32 s11, s11, 0
	s_mov_b32 m0, s12
	s_add_u32 s12, s12, 0x2000
	global_load_lds_dwordx4 v68, s[10:11]
	s_add_u32 s10, s10, 0x2c000
	s_addc_u32 s11, s11, 0
	s_mov_b32 m0, s12
	s_add_u32 s12, s12, 0x2000
	global_load_lds_dwordx4 v68, s[10:11]
	s_add_u32 s10, s10, 0x2c000
	s_addc_u32 s11, s11, 0
	s_mov_b32 m0, s12
	s_add_u32 s12, s12, 0x2000
	global_load_lds_dwordx4 v68, s[10:11]
	s_add_u32 s10, s10, 0x2c000
	s_addc_u32 s11, s11, 0
	s_mov_b32 m0, s12
	s_add_u32 s12, s12, 0x2000
	global_load_lds_dwordx4 v68, s[10:11]
	s_add_u32 s10, s10, 0x2c000
	s_addc_u32 s11, s11, 0
	s_mov_b32 m0, s12
	s_add_u32 s12, s12, 0x2000
	global_load_lds_dwordx4 v68, s[10:11]
	s_add_u32 s10, s10, 0x2c000
	s_addc_u32 s11, s11, 0
	s_mov_b32 m0, s12
	s_add_u32 s12, s12, 0x2000
	global_load_lds_dwordx4 v68, s[10:11]
	s_add_u32 s10, s10, 0x2c000
	s_addc_u32 s11, s11, 0
	s_add_u32 s38, s38, 0x160000
	s_addc_u32 s39, s39, 0
	s_waitcnt vmcnt(0)
	s_barrier
	ds_read_b128 v[84:87], v70 offset:0
	ds_read_b128 v[88:91], v70 offset:8192
	ds_read_b128 v[92:95], v74 offset:0
	ds_read_b128 v[96:99], v74 offset:8192
	ds_read_b128 v[100:103], v74 offset:16384
	ds_read_b128 v[104:107], v74 offset:24576
	ds_read_b128 v[108:111], v71 offset:0
	ds_read_b128 v[112:115], v71 offset:8192
	ds_read_b128 v[116:119], v75 offset:0
	ds_read_b128 v[120:123], v75 offset:8192
	ds_read_b128 v[124:127], v75 offset:16384
	ds_read_b128 v[128:131], v75 offset:24576
	s_waitcnt lgkmcnt(6)
	v_mfma_f32_16x16x32_bf16 v[0:3], v[92:95], v[84:87], 0
	v_mfma_f32_16x16x32_bf16 v[4:7], v[96:99], v[84:87], 0
	v_mfma_f32_16x16x32_bf16 v[8:11], v[100:103], v[84:87], 0
	v_mfma_f32_16x16x32_bf16 v[12:15], v[104:107], v[84:87], 0
	v_mfma_f32_16x16x32_bf16 v[32:35], v[92:95], v[88:91], 0
	v_mfma_f32_16x16x32_bf16 v[36:39], v[96:99], v[88:91], 0
	v_mfma_f32_16x16x32_bf16 v[40:43], v[100:103], v[88:91], 0
	v_mfma_f32_16x16x32_bf16 v[44:47], v[104:107], v[88:91], 0
	ds_read_b128 v[84:87], v72 offset:0
	ds_read_b128 v[88:91], v72 offset:8192
	ds_read_b128 v[92:95], v76 offset:0
	ds_read_b128 v[96:99], v76 offset:8192
	ds_read_b128 v[100:103], v76 offset:16384
	ds_read_b128 v[104:107], v76 offset:24576
	s_waitcnt lgkmcnt(6)
	v_mfma_f32_16x16x32_bf16 v[0:3], v[116:119], v[108:111], v[0:3]
	v_mfma_f32_16x16x32_bf16 v[4:7], v[120:123], v[108:111], v[4:7]
	v_mfma_f32_16x16x32_bf16 v[8:11], v[124:127], v[108:111], v[8:11]
	v_mfma_f32_16x16x32_bf16 v[12:15], v[128:131], v[108:111], v[12:15]
	v_mfma_f32_16x16x32_bf16 v[32:35], v[116:119], v[112:115], v[32:35]
	v_mfma_f32_16x16x32_bf16 v[36:39], v[120:123], v[112:115], v[36:39]
	v_mfma_f32_16x16x32_bf16 v[40:43], v[124:127], v[112:115], v[40:43]
	v_mfma_f32_16x16x32_bf16 v[44:47], v[128:131], v[112:115], v[44:47]
	ds_read_b128 v[108:111], v73 offset:0
	ds_read_b128 v[112:115], v73 offset:8192
	ds_read_b128 v[116:119], v77 offset:0
	ds_read_b128 v[120:123], v77 offset:8192
	ds_read_b128 v[124:127], v77 offset:16384
	ds_read_b128 v[128:131], v77 offset:24576
	s_waitcnt lgkmcnt(6)
	v_mfma_f32_16x16x32_bf16 v[0:3], v[92:95], v[84:87], v[0:3]
	v_mfma_f32_16x16x32_bf16 v[4:7], v[96:99], v[84:87], v[4:7]
	v_mfma_f32_16x16x32_bf16 v[8:11], v[100:103], v[84:87], v[8:11]
	v_mfma_f32_16x16x32_bf16 v[12:15], v[104:107], v[84:87], v[12:15]
	v_mfma_f32_16x16x32_bf16 v[32:35], v[92:95], v[88:91], v[32:35]
	v_mfma_f32_16x16x32_bf16 v[36:39], v[96:99], v[88:91], v[36:39]
	v_mfma_f32_16x16x32_bf16 v[40:43], v[100:103], v[88:91], v[40:43]
	v_mfma_f32_16x16x32_bf16 v[44:47], v[104:107], v[88:91], v[44:47]
	ds_read_b128 v[84:87], v70 offset:256
	ds_read_b128 v[88:91], v70 offset:8448
	ds_read_b128 v[92:95], v74 offset:256
	ds_read_b128 v[96:99], v74 offset:8448
	ds_read_b128 v[100:103], v74 offset:16640
	ds_read_b128 v[104:107], v74 offset:24832
	s_waitcnt lgkmcnt(6)
	v_mfma_f32_16x16x32_bf16 v[0:3], v[116:119], v[108:111], v[0:3]
	v_mfma_f32_16x16x32_bf16 v[4:7], v[120:123], v[108:111], v[4:7]
	v_mfma_f32_16x16x32_bf16 v[8:11], v[124:127], v[108:111], v[8:11]
	v_mfma_f32_16x16x32_bf16 v[12:15], v[128:131], v[108:111], v[12:15]
	v_mfma_f32_16x16x32_bf16 v[32:35], v[116:119], v[112:115], v[32:35]
	v_mfma_f32_16x16x32_bf16 v[36:39], v[120:123], v[112:115], v[36:39]
	v_mfma_f32_16x16x32_bf16 v[40:43], v[124:127], v[112:115], v[40:43]
	v_mfma_f32_16x16x32_bf16 v[44:47], v[128:131], v[112:115], v[44:47]
	ds_read_b128 v[108:111], v71 offset:256
	ds_read_b128 v[112:115], v71 offset:8448
	ds_read_b128 v[116:119], v75 offset:256
	ds_read_b128 v[120:123], v75 offset:8448
	ds_read_b128 v[124:127], v75 offset:16640
	ds_read_b128 v[128:131], v75 offset:24832
	s_waitcnt lgkmcnt(6)
	v_mfma_f32_16x16x32_bf16 v[0:3], v[92:95], v[84:87], v[0:3]
	v_mfma_f32_16x16x32_bf16 v[4:7], v[96:99], v[84:87], v[4:7]
	v_mfma_f32_16x16x32_bf16 v[8:11], v[100:103], v[84:87], v[8:11]
	v_mfma_f32_16x16x32_bf16 v[12:15], v[104:107], v[84:87], v[12:15]
	v_mfma_f32_16x16x32_bf16 v[32:35], v[92:95], v[88:91], v[32:35]
	v_mfma_f32_16x16x32_bf16 v[36:39], v[96:99], v[88:91], v[36:39]
	v_mfma_f32_16x16x32_bf16 v[40:43], v[100:103], v[88:91], v[40:43]
	v_mfma_f32_16x16x32_bf16 v[44:47], v[104:107], v[88:91], v[44:47]
	ds_read_b128 v[84:87], v72 offset:256
	ds_read_b128 v[88:91], v72 offset:8448
	ds_read_b128 v[92:95], v76 offset:256
	ds_read_b128 v[96:99], v76 offset:8448
	ds_read_b128 v[100:103], v76 offset:16640
	ds_read_b128 v[104:107], v76 offset:24832
	s_waitcnt lgkmcnt(6)
	v_mfma_f32_16x16x32_bf16 v[0:3], v[116:119], v[108:111], v[0:3]
	v_mfma_f32_16x16x32_bf16 v[4:7], v[120:123], v[108:111], v[4:7]
	v_mfma_f32_16x16x32_bf16 v[8:11], v[124:127], v[108:111], v[8:11]
	v_mfma_f32_16x16x32_bf16 v[12:15], v[128:131], v[108:111], v[12:15]
	v_mfma_f32_16x16x32_bf16 v[32:35], v[116:119], v[112:115], v[32:35]
	v_mfma_f32_16x16x32_bf16 v[36:39], v[120:123], v[112:115], v[36:39]
	v_mfma_f32_16x16x32_bf16 v[40:43], v[124:127], v[112:115], v[40:43]
	v_mfma_f32_16x16x32_bf16 v[44:47], v[128:131], v[112:115], v[44:47]
	ds_read_b128 v[108:111], v73 offset:256
	ds_read_b128 v[112:115], v73 offset:8448
	ds_read_b128 v[116:119], v77 offset:256
	ds_read_b128 v[120:123], v77 offset:8448
	ds_read_b128 v[124:127], v77 offset:16640
	ds_read_b128 v[128:131], v77 offset:24832
	s_waitcnt lgkmcnt(6)
	v_mfma_f32_16x16x32_bf16 v[0:3], v[92:95], v[84:87], v[0:3]
	v_mfma_f32_16x16x32_bf16 v[4:7], v[96:99], v[84:87], v[4:7]
	v_mfma_f32_16x16x32_bf16 v[8:11], v[100:103], v[84:87], v[8:11]
	v_mfma_f32_16x16x32_bf16 v[12:15], v[104:107], v[84:87], v[12:15]
	v_mfma_f32_16x16x32_bf16 v[32:35], v[92:95], v[88:91], v[32:35]
	v_mfma_f32_16x16x32_bf16 v[36:39], v[96:99], v[88:91], v[36:39]
	v_mfma_f32_16x16x32_bf16 v[40:43], v[100:103], v[88:91], v[40:43]
	v_mfma_f32_16x16x32_bf16 v[44:47], v[104:107], v[88:91], v[44:47]
	s_waitcnt lgkmcnt(0)
	v_mfma_f32_16x16x32_bf16 v[0:3], v[116:119], v[108:111], v[0:3]
	v_mfma_f32_16x16x32_bf16 v[4:7], v[120:123], v[108:111], v[4:7]
	v_mfma_f32_16x16x32_bf16 v[8:11], v[124:127], v[108:111], v[8:11]
	v_mfma_f32_16x16x32_bf16 v[12:15], v[128:131], v[108:111], v[12:15]
	v_mfma_f32_16x16x32_bf16 v[32:35], v[116:119], v[112:115], v[32:35]
	v_mfma_f32_16x16x32_bf16 v[36:39], v[120:123], v[112:115], v[36:39]
	v_mfma_f32_16x16x32_bf16 v[40:43], v[124:127], v[112:115], v[40:43]
	v_mfma_f32_16x16x32_bf16 v[44:47], v[128:131], v[112:115], v[44:47]
	s_barrier
	s_mov_b64 s[10:11], s[38:39]
	s_add_u32 s12, s59, 0x10000
	s_mov_b32 m0, s12
	s_add_u32 s12, s12, 0x2000
	global_load_lds_dwordx4 v68, s[10:11]
	s_add_u32 s10, s10, 0x2c000
	s_addc_u32 s11, s11, 0
	s_mov_b32 m0, s12
	s_add_u32 s12, s12, 0x2000
	global_load_lds_dwordx4 v68, s[10:11]
	s_add_u32 s10, s10, 0x2c000
	s_addc_u32 s11, s11, 0
	s_mov_b32 m0, s12
	s_add_u32 s12, s12, 0x2000
	global_load_lds_dwordx4 v68, s[10:11]
	s_add_u32 s10, s10, 0x2c000
	s_addc_u32 s11, s11, 0
	s_mov_b32 m0, s12
	s_add_u32 s12, s12, 0x2000
	global_load_lds_dwordx4 v68, s[10:11]
	s_add_u32 s10, s10, 0x2c000
	s_addc_u32 s11, s11, 0
	s_mov_b32 m0, s12
	s_add_u32 s12, s12, 0x2000
	global_load_lds_dwordx4 v68, s[10:11]
	s_add_u32 s10, s10, 0x2c000
	s_addc_u32 s11, s11, 0
	s_mov_b32 m0, s12
	s_add_u32 s12, s12, 0x2000
	global_load_lds_dwordx4 v68, s[10:11]
	s_add_u32 s10, s10, 0x2c000
	s_addc_u32 s11, s11, 0
	s_mov_b32 m0, s12
	s_add_u32 s12, s12, 0x2000
	global_load_lds_dwordx4 v68, s[10:11]
	s_add_u32 s10, s10, 0x2c000
	s_addc_u32 s11, s11, 0
	s_mov_b32 m0, s12
	s_add_u32 s12, s12, 0x2000
	global_load_lds_dwordx4 v68, s[10:11]
	s_add_u32 s10, s10, 0x2c000
	s_addc_u32 s11, s11, 0
	s_waitcnt vmcnt(0)
	s_barrier
	ds_read_b128 v[84:87], v70 offset:0
	ds_read_b128 v[88:91], v70 offset:8192
	ds_read_b128 v[92:95], v74 offset:0
	ds_read_b128 v[96:99], v74 offset:8192
	ds_read_b128 v[100:103], v74 offset:16384
	ds_read_b128 v[104:107], v74 offset:24576
	ds_read_b128 v[108:111], v71 offset:0
	ds_read_b128 v[112:115], v71 offset:8192
	ds_read_b128 v[116:119], v75 offset:0
	ds_read_b128 v[120:123], v75 offset:8192
	ds_read_b128 v[124:127], v75 offset:16384
	ds_read_b128 v[128:131], v75 offset:24576
	s_waitcnt lgkmcnt(6)
	v_mfma_f32_16x16x32_bf16 v[16:19], v[92:95], v[84:87], 0
	v_mfma_f32_16x16x32_bf16 v[20:23], v[96:99], v[84:87], 0
	v_mfma_f32_16x16x32_bf16 v[24:27], v[100:103], v[84:87], 0
	v_mfma_f32_16x16x32_bf16 v[28:31], v[104:107], v[84:87], 0
	v_mfma_f32_16x16x32_bf16 v[48:51], v[92:95], v[88:91], 0
	v_mfma_f32_16x16x32_bf16 v[52:55], v[96:99], v[88:91], 0
	v_mfma_f32_16x16x32_bf16 v[56:59], v[100:103], v[88:91], 0
	v_mfma_f32_16x16x32_bf16 v[60:63], v[104:107], v[88:91], 0
	ds_read_b128 v[84:87], v72 offset:0
	ds_read_b128 v[88:91], v72 offset:8192
	ds_read_b128 v[92:95], v76 offset:0
	ds_read_b128 v[96:99], v76 offset:8192
	ds_read_b128 v[100:103], v76 offset:16384
	ds_read_b128 v[104:107], v76 offset:24576
	s_waitcnt lgkmcnt(6)
	v_mfma_f32_16x16x32_bf16 v[16:19], v[116:119], v[108:111], v[16:19]
	v_mfma_f32_16x16x32_bf16 v[20:23], v[120:123], v[108:111], v[20:23]
	v_mfma_f32_16x16x32_bf16 v[24:27], v[124:127], v[108:111], v[24:27]
	v_mfma_f32_16x16x32_bf16 v[28:31], v[128:131], v[108:111], v[28:31]
	v_mfma_f32_16x16x32_bf16 v[48:51], v[116:119], v[112:115], v[48:51]
	v_mfma_f32_16x16x32_bf16 v[52:55], v[120:123], v[112:115], v[52:55]
	v_mfma_f32_16x16x32_bf16 v[56:59], v[124:127], v[112:115], v[56:59]
	v_mfma_f32_16x16x32_bf16 v[60:63], v[128:131], v[112:115], v[60:63]
	ds_read_b128 v[108:111], v73 offset:0
	ds_read_b128 v[112:115], v73 offset:8192
	ds_read_b128 v[116:119], v77 offset:0
	ds_read_b128 v[120:123], v77 offset:8192
	ds_read_b128 v[124:127], v77 offset:16384
	ds_read_b128 v[128:131], v77 offset:24576
	s_waitcnt lgkmcnt(6)
	v_mfma_f32_16x16x32_bf16 v[16:19], v[92:95], v[84:87], v[16:19]
	v_mfma_f32_16x16x32_bf16 v[20:23], v[96:99], v[84:87], v[20:23]
	v_mfma_f32_16x16x32_bf16 v[24:27], v[100:103], v[84:87], v[24:27]
	v_mfma_f32_16x16x32_bf16 v[28:31], v[104:107], v[84:87], v[28:31]
	v_mfma_f32_16x16x32_bf16 v[48:51], v[92:95], v[88:91], v[48:51]
	v_mfma_f32_16x16x32_bf16 v[52:55], v[96:99], v[88:91], v[52:55]
	v_mfma_f32_16x16x32_bf16 v[56:59], v[100:103], v[88:91], v[56:59]
	v_mfma_f32_16x16x32_bf16 v[60:63], v[104:107], v[88:91], v[60:63]
	ds_read_b128 v[84:87], v70 offset:256
	ds_read_b128 v[88:91], v70 offset:8448
	ds_read_b128 v[92:95], v74 offset:256
	ds_read_b128 v[96:99], v74 offset:8448
	ds_read_b128 v[100:103], v74 offset:16640
	ds_read_b128 v[104:107], v74 offset:24832
	s_waitcnt lgkmcnt(6)
	v_mfma_f32_16x16x32_bf16 v[16:19], v[116:119], v[108:111], v[16:19]
	v_mfma_f32_16x16x32_bf16 v[20:23], v[120:123], v[108:111], v[20:23]
	v_mfma_f32_16x16x32_bf16 v[24:27], v[124:127], v[108:111], v[24:27]
	v_mfma_f32_16x16x32_bf16 v[28:31], v[128:131], v[108:111], v[28:31]
	v_mfma_f32_16x16x32_bf16 v[48:51], v[116:119], v[112:115], v[48:51]
	v_mfma_f32_16x16x32_bf16 v[52:55], v[120:123], v[112:115], v[52:55]
	v_mfma_f32_16x16x32_bf16 v[56:59], v[124:127], v[112:115], v[56:59]
	v_mfma_f32_16x16x32_bf16 v[60:63], v[128:131], v[112:115], v[60:63]
	ds_read_b128 v[108:111], v71 offset:256
	ds_read_b128 v[112:115], v71 offset:8448
	ds_read_b128 v[116:119], v75 offset:256
	ds_read_b128 v[120:123], v75 offset:8448
	ds_read_b128 v[124:127], v75 offset:16640
	ds_read_b128 v[128:131], v75 offset:24832
	s_waitcnt lgkmcnt(6)
	v_mfma_f32_16x16x32_bf16 v[16:19], v[92:95], v[84:87], v[16:19]
	v_mfma_f32_16x16x32_bf16 v[20:23], v[96:99], v[84:87], v[20:23]
	v_mfma_f32_16x16x32_bf16 v[24:27], v[100:103], v[84:87], v[24:27]
	v_mfma_f32_16x16x32_bf16 v[28:31], v[104:107], v[84:87], v[28:31]
	v_mfma_f32_16x16x32_bf16 v[48:51], v[92:95], v[88:91], v[48:51]
	v_mfma_f32_16x16x32_bf16 v[52:55], v[96:99], v[88:91], v[52:55]
	v_mfma_f32_16x16x32_bf16 v[56:59], v[100:103], v[88:91], v[56:59]
	v_mfma_f32_16x16x32_bf16 v[60:63], v[104:107], v[88:91], v[60:63]
	ds_read_b128 v[84:87], v72 offset:256
	ds_read_b128 v[88:91], v72 offset:8448
	ds_read_b128 v[92:95], v76 offset:256
	ds_read_b128 v[96:99], v76 offset:8448
	ds_read_b128 v[100:103], v76 offset:16640
	ds_read_b128 v[104:107], v76 offset:24832
	s_waitcnt lgkmcnt(6)
	v_mfma_f32_16x16x32_bf16 v[16:19], v[116:119], v[108:111], v[16:19]
	v_mfma_f32_16x16x32_bf16 v[20:23], v[120:123], v[108:111], v[20:23]
	v_mfma_f32_16x16x32_bf16 v[24:27], v[124:127], v[108:111], v[24:27]
	v_mfma_f32_16x16x32_bf16 v[28:31], v[128:131], v[108:111], v[28:31]
	v_mfma_f32_16x16x32_bf16 v[48:51], v[116:119], v[112:115], v[48:51]
	v_mfma_f32_16x16x32_bf16 v[52:55], v[120:123], v[112:115], v[52:55]
	v_mfma_f32_16x16x32_bf16 v[56:59], v[124:127], v[112:115], v[56:59]
	v_mfma_f32_16x16x32_bf16 v[60:63], v[128:131], v[112:115], v[60:63]
	ds_read_b128 v[108:111], v73 offset:256
	ds_read_b128 v[112:115], v73 offset:8448
	ds_read_b128 v[116:119], v77 offset:256
	ds_read_b128 v[120:123], v77 offset:8448
	ds_read_b128 v[124:127], v77 offset:16640
	ds_read_b128 v[128:131], v77 offset:24832
	s_waitcnt lgkmcnt(6)
	v_mfma_f32_16x16x32_bf16 v[16:19], v[92:95], v[84:87], v[16:19]
	v_mfma_f32_16x16x32_bf16 v[20:23], v[96:99], v[84:87], v[20:23]
	v_mfma_f32_16x16x32_bf16 v[24:27], v[100:103], v[84:87], v[24:27]
	v_mfma_f32_16x16x32_bf16 v[28:31], v[104:107], v[84:87], v[28:31]
	v_mfma_f32_16x16x32_bf16 v[48:51], v[92:95], v[88:91], v[48:51]
	v_mfma_f32_16x16x32_bf16 v[52:55], v[96:99], v[88:91], v[52:55]
	v_mfma_f32_16x16x32_bf16 v[56:59], v[100:103], v[88:91], v[56:59]
	v_mfma_f32_16x16x32_bf16 v[60:63], v[104:107], v[88:91], v[60:63]
	s_waitcnt lgkmcnt(0)
	v_mfma_f32_16x16x32_bf16 v[16:19], v[116:119], v[108:111], v[16:19]
	v_mfma_f32_16x16x32_bf16 v[20:23], v[120:123], v[108:111], v[20:23]
	v_mfma_f32_16x16x32_bf16 v[24:27], v[124:127], v[108:111], v[24:27]
	v_mfma_f32_16x16x32_bf16 v[28:31], v[128:131], v[108:111], v[28:31]
	v_mfma_f32_16x16x32_bf16 v[48:51], v[116:119], v[112:115], v[48:51]
	v_mfma_f32_16x16x32_bf16 v[52:55], v[120:123], v[112:115], v[52:55]
	v_mfma_f32_16x16x32_bf16 v[56:59], v[124:127], v[112:115], v[56:59]
	v_mfma_f32_16x16x32_bf16 v[60:63], v[128:131], v[112:115], v[60:63]
	s_nop 7
	global_store_dwordx4 v69, v[0:3], s[40:41] offset:0
	global_store_dwordx4 v69, v[4:7], s[40:41] offset:64
	global_store_dwordx4 v69, v[8:11], s[40:41] offset:128
	global_store_dwordx4 v69, v[12:15], s[40:41] offset:192
	global_store_dwordx4 v69, v[16:19], s[40:41] offset:512
	global_store_dwordx4 v69, v[20:23], s[40:41] offset:576
	global_store_dwordx4 v69, v[24:27], s[40:41] offset:640
	global_store_dwordx4 v69, v[28:31], s[40:41] offset:704
	global_store_dwordx4 v69, v[32:35], s[42:43] offset:0
	global_store_dwordx4 v69, v[36:39], s[42:43] offset:64
	global_store_dwordx4 v69, v[40:43], s[42:43] offset:128
	global_store_dwordx4 v69, v[44:47], s[42:43] offset:192
	global_store_dwordx4 v69, v[48:51], s[42:43] offset:512
	global_store_dwordx4 v69, v[52:55], s[42:43] offset:576
	global_store_dwordx4 v69, v[56:59], s[42:43] offset:640
	global_store_dwordx4 v69, v[60:63], s[42:43] offset:704
